# LN sample rows: the 64 LDS reads that combine the split-K partial slices are issued in batches of 8 with counted waits
# baseline (speedup 1.0000x reference)
; #define LAS __attribute__((address_space(3)))
; #define GAS __attribute__((address_space(1)))
; __device__ __forceinline__ float bflo(unsigned u) { return __uint_as_float(u << 16); }
; __device__ __forceinline__ float bfhi(unsigned u) { return __uint_as_float(u & 0xffff0000u); }
; __device__ __forceinline__ void ln_phase(const bf16_t* Z, const bf16_t* RES, const float* part, int nsl, const float* g, const float* b, bf16_t* XB, float* outp, float* outs, int gw, int NGW, int lane,
;                                          LAS float* scr, int wave, int bid, int nblk) {
;     ...
;         for (int j = 0; j < 8; ++j) *(LAS f32x4*)(scr + wave * 2048 + (lane + 64 * j) * 4) = acc[j];
;         __syncthreads();
;         if (wave == 0) { const GAS u32x2* z_ = (const GAS u32x2*)(RES + (size_t)(MP + r) * DM) + lane; f32x4 v[8];
; #pragma unroll
;             for (int j = 0; j < 8; ++j) { const u32x2 w = z_[64 * j]; v[j] = (f32x4){ALPHA * bflo(w.x), ALPHA * bfhi(w.x), ALPHA * bflo(w.y), ALPHA * bfhi(w.y)}; }
; #pragma unroll
;             for (int w8 = 0; w8 < 8; ++w8)
; #pragma unroll
;                 for (int j = 0; j < 8; ++j) v[j] += *(LAS const f32x4*)(scr + w8 * 2048 + (lane + 64 * j) * 4);
.LBB0_127:
	v_add_u32_e32 v98, s67, v0
	s_and_b64 vcc, exec, s[80:81]
	ds_write_b128 v98, v[94:97]
	ds_write_b128 v98, v[90:93] offset:1024
	ds_write_b128 v98, v[86:89] offset:2048
	ds_write_b128 v98, v[82:85] offset:3072
	ds_write_b128 v98, v[78:81] offset:4096
	ds_write_b128 v98, v[74:77] offset:5120
	ds_write_b128 v98, v[70:73] offset:6144
	ds_write_b128 v98, v[66:69] offset:7168
	s_waitcnt vmcnt(0) lgkmcnt(0)
	s_barrier
	s_cbranch_vccz .LBB0_123
	s_ashr_i32 s39, s38, 31
	s_lshl_b64 s[0:1], s[38:39], 12
	s_add_u32 s0, s30, s0
	s_addc_u32 s1, s31, s1
	v_lshlrev_b32_e32 v66, 3, v102
	v_mov_b32_e32 v67, v1
	v_lshl_add_u64 v[68:69], s[0:1], 0, v[66:67]
	s_mov_b64 s[0:1], 0x4000000
	v_lshl_add_u64 v[66:67], v[68:69], 0, s[0:1]
	v_add_co_u32_e32 v68, vcc, 0x4000000, v68
	s_nop 1
	v_addc_co_u32_e32 v69, vcc, 0, v69, vcc
	global_load_dwordx2 v[222:223], v[68:69], off
	global_load_dwordx2 v[224:225], v[66:67], off offset:512
	global_load_dwordx2 v[226:227], v[66:67], off offset:1024
	global_load_dwordx2 v[228:229], v[66:67], off offset:1536
	global_load_dwordx2 v[142:143], v[66:67], off offset:2048
	global_load_dwordx2 v[144:145], v[66:67], off offset:2560
	global_load_dwordx2 v[146:147], v[66:67], off offset:3072
	global_load_dwordx2 v[148:149], v[66:67], off offset:3584
	s_waitcnt vmcnt(0)
	v_lshlrev_b32_e32 v74, 16, v222
	v_and_b32_e32 v75, 0xffff0000, v222
	v_lshlrev_b32_e32 v76, 16, v223
	v_and_b32_e32 v77, 0xffff0000, v223
	v_lshlrev_b32_e32 v78, 16, v224
	v_and_b32_e32 v79, 0xffff0000, v224
	v_lshlrev_b32_e32 v80, 16, v225
	v_and_b32_e32 v81, 0xffff0000, v225
	v_lshlrev_b32_e32 v82, 16, v226
	v_and_b32_e32 v83, 0xffff0000, v226
	v_lshlrev_b32_e32 v84, 16, v227
	v_and_b32_e32 v85, 0xffff0000, v227
	v_lshlrev_b32_e32 v86, 16, v228
	v_and_b32_e32 v87, 0xffff0000, v228
	v_lshlrev_b32_e32 v88, 16, v229
	v_and_b32_e32 v89, 0xffff0000, v229
	v_lshlrev_b32_e32 v90, 16, v142
	v_and_b32_e32 v91, 0xffff0000, v142
	v_lshlrev_b32_e32 v92, 16, v143
	v_and_b32_e32 v93, 0xffff0000, v143
	v_lshlrev_b32_e32 v94, 16, v144
	v_and_b32_e32 v95, 0xffff0000, v144
	v_lshlrev_b32_e32 v96, 16, v145
	v_and_b32_e32 v97, 0xffff0000, v145
	v_lshlrev_b32_e32 v98, 16, v146
	v_and_b32_e32 v99, 0xffff0000, v146
	v_lshlrev_b32_e32 v100, 16, v147
	v_and_b32_e32 v101, 0xffff0000, v147
	v_lshlrev_b32_e32 v104, 16, v148
	v_and_b32_e32 v105, 0xffff0000, v148
	v_lshlrev_b32_e32 v106, 16, v149
	v_and_b32_e32 v107, 0xffff0000, v149
	ds_read_b128 v[190:193], v103
	ds_read_b128 v[194:197], v103 offset:1024
	ds_read_b128 v[198:201], v103 offset:2048
	ds_read_b128 v[202:205], v103 offset:3072
	ds_read_b128 v[206:209], v103 offset:4096
	ds_read_b128 v[210:213], v103 offset:5120
	ds_read_b128 v[214:217], v103 offset:6144
	ds_read_b128 v[218:221], v103 offset:7168
	s_waitcnt lgkmcnt(7)
	v_pk_fma_f32 v[74:75], v[74:75], s[52:53], v[190:191] op_sel_hi:[1, 0, 1]
	v_pk_fma_f32 v[76:77], v[76:77], s[52:53], v[192:193] op_sel_hi:[1, 0, 1]
	s_waitcnt lgkmcnt(6)
	v_pk_fma_f32 v[78:79], v[78:79], s[52:53], v[194:195] op_sel_hi:[1, 0, 1]
	v_pk_fma_f32 v[80:81], v[80:81], s[52:53], v[196:197] op_sel_hi:[1, 0, 1]
	s_waitcnt lgkmcnt(5)
	v_pk_fma_f32 v[108:109], v[82:83], s[52:53], v[198:199] op_sel_hi:[1, 0, 1]
	v_pk_fma_f32 v[82:83], v[84:85], s[52:53], v[200:201] op_sel_hi:[1, 0, 1]
	s_waitcnt lgkmcnt(4)
	v_pk_fma_f32 v[110:111], v[86:87], s[52:53], v[202:203] op_sel_hi:[1, 0, 1]
	v_pk_fma_f32 v[112:113], v[88:89], s[52:53], v[204:205] op_sel_hi:[1, 0, 1]
	s_waitcnt lgkmcnt(3)
	v_pk_fma_f32 v[114:115], v[90:91], s[52:53], v[206:207] op_sel_hi:[1, 0, 1]
	v_pk_fma_f32 v[116:117], v[92:93], s[52:53], v[208:209] op_sel_hi:[1, 0, 1]
	s_waitcnt lgkmcnt(2)
	v_pk_fma_f32 v[118:119], v[94:95], s[52:53], v[210:211] op_sel_hi:[1, 0, 1]
	v_pk_fma_f32 v[120:121], v[96:97], s[52:53], v[212:213] op_sel_hi:[1, 0, 1]
	s_waitcnt lgkmcnt(1)
	v_pk_fma_f32 v[98:99], v[98:99], s[52:53], v[214:215] op_sel_hi:[1, 0, 1]
	v_pk_fma_f32 v[100:101], v[100:101], s[52:53], v[216:217] op_sel_hi:[1, 0, 1]
	s_waitcnt lgkmcnt(0)
	v_pk_fma_f32 v[94:95], v[104:105], s[52:53], v[218:219] op_sel_hi:[1, 0, 1]
	v_pk_fma_f32 v[96:97], v[106:107], s[52:53], v[220:221] op_sel_hi:[1, 0, 1]
	ds_read_b128 v[190:193], v103 offset:8192
	ds_read_b128 v[194:197], v103 offset:13312
	ds_read_b128 v[198:201], v103 offset:9216
	ds_read_b128 v[202:205], v103 offset:10240
	ds_read_b128 v[206:209], v103 offset:11264
	ds_read_b128 v[210:213], v103 offset:12288
	ds_read_b128 v[214:217], v103 offset:14336
	ds_read_b128 v[218:221], v103 offset:15360
	s_waitcnt lgkmcnt(7)
	v_pk_add_f32 v[90:91], v[76:77], v[192:193]
	v_pk_add_f32 v[92:93], v[74:75], v[190:191]
	s_waitcnt lgkmcnt(5)
	v_pk_add_f32 v[86:87], v[80:81], v[200:201]
	v_pk_add_f32 v[88:89], v[78:79], v[198:199]
	s_waitcnt lgkmcnt(4)
	v_pk_add_f32 v[82:83], v[82:83], v[204:205]
	v_pk_add_f32 v[84:85], v[108:109], v[202:203]
	s_waitcnt lgkmcnt(3)
	v_pk_add_f32 v[78:79], v[112:113], v[208:209]
	v_pk_add_f32 v[80:81], v[110:111], v[206:207]
	s_waitcnt lgkmcnt(2)
	v_pk_add_f32 v[74:75], v[116:117], v[212:213]
	v_pk_add_f32 v[76:77], v[114:115], v[210:211]
	v_pk_add_f32 v[70:71], v[120:121], v[196:197]
	v_pk_add_f32 v[72:73], v[118:119], v[194:195]
	s_waitcnt lgkmcnt(1)
	v_pk_add_f32 v[106:107], v[100:101], v[216:217]
	v_pk_add_f32 v[104:105], v[98:99], v[214:215]
	s_waitcnt lgkmcnt(0)
	v_pk_add_f32 v[100:101], v[96:97], v[220:221]
	v_pk_add_f32 v[98:99], v[94:95], v[218:219]
	ds_read_b128 v[190:193], v103 offset:16384
	ds_read_b128 v[194:197], v103 offset:17408
	ds_read_b128 v[198:201], v103 offset:18432
	ds_read_b128 v[202:205], v103 offset:19456
	ds_read_b128 v[206:209], v103 offset:20480
	ds_read_b128 v[210:213], v103 offset:21504
	ds_read_b128 v[214:217], v103 offset:22528
	ds_read_b128 v[218:221], v103 offset:23552
	s_waitcnt lgkmcnt(7)
; #define LAS __attribute__((address_space(3)))
; __device__ __forceinline__ void ln_phase(const bf16_t* Z, const bf16_t* RES, const float* part, int nsl, const float* g, const float* b, bf16_t* XB, float* outp, float* outs, int gw, int NGW, int lane,
;                                          LAS float* scr, int wave, int bid, int nblk) {
;     ...
;             for (int w8 = 0; w8 < 8; ++w8)
; #pragma unroll
;                 for (int j = 0; j < 8; ++j) v[j] += *(LAS const f32x4*)(scr + w8 * 2048 + (lane + 64 * j) * 4);
	v_pk_add_f32 v[94:95], v[92:93], v[190:191]
	v_pk_add_f32 v[96:97], v[90:91], v[192:193]
	s_waitcnt lgkmcnt(6)
	v_pk_add_f32 v[90:91], v[88:89], v[194:195]
	v_pk_add_f32 v[92:93], v[86:87], v[196:197]
	s_waitcnt lgkmcnt(5)
	v_pk_add_f32 v[86:87], v[84:85], v[198:199]
	v_pk_add_f32 v[88:89], v[82:83], v[200:201]
	s_waitcnt lgkmcnt(4)
	v_pk_add_f32 v[82:83], v[80:81], v[202:203]
	v_pk_add_f32 v[84:85], v[78:79], v[204:205]
	s_waitcnt lgkmcnt(3)
	v_pk_add_f32 v[78:79], v[76:77], v[206:207]
	v_pk_add_f32 v[80:81], v[74:75], v[208:209]
	s_waitcnt lgkmcnt(2)
	v_pk_add_f32 v[74:75], v[72:73], v[210:211]
	v_pk_add_f32 v[76:77], v[70:71], v[212:213]
	s_waitcnt lgkmcnt(1)
	v_pk_add_f32 v[104:105], v[104:105], v[214:215]
	v_pk_add_f32 v[106:107], v[106:107], v[216:217]
	s_waitcnt lgkmcnt(0)
	v_pk_add_f32 v[98:99], v[98:99], v[218:219]
	v_pk_add_f32 v[100:101], v[100:101], v[220:221]
	ds_read_b128 v[190:193], v103 offset:24576
	ds_read_b128 v[194:197], v103 offset:25600
	ds_read_b128 v[198:201], v103 offset:26624
	ds_read_b128 v[202:205], v103 offset:27648
	ds_read_b128 v[206:209], v103 offset:28672
	ds_read_b128 v[210:213], v103 offset:29696
	ds_read_b128 v[214:217], v103 offset:30720
	ds_read_b128 v[218:221], v103 offset:31744
	s_waitcnt lgkmcnt(7)
	v_pk_add_f32 v[96:97], v[96:97], v[192:193]
	v_pk_add_f32 v[94:95], v[94:95], v[190:191]
	s_waitcnt lgkmcnt(6)
	v_pk_add_f32 v[92:93], v[92:93], v[196:197]
	v_pk_add_f32 v[90:91], v[90:91], v[194:195]
	s_waitcnt lgkmcnt(5)
	v_pk_add_f32 v[88:89], v[88:89], v[200:201]
	v_pk_add_f32 v[86:87], v[86:87], v[198:199]
	s_waitcnt lgkmcnt(4)
	v_pk_add_f32 v[84:85], v[84:85], v[204:205]
	v_pk_add_f32 v[82:83], v[82:83], v[202:203]
	s_waitcnt lgkmcnt(3)
	v_pk_add_f32 v[80:81], v[80:81], v[208:209]
	v_pk_add_f32 v[78:79], v[78:79], v[206:207]
	s_waitcnt lgkmcnt(2)
	v_pk_add_f32 v[76:77], v[76:77], v[212:213]
	v_pk_add_f32 v[74:75], v[74:75], v[210:211]
	s_waitcnt lgkmcnt(1)
	v_pk_add_f32 v[106:107], v[106:107], v[216:217]
	v_pk_add_f32 v[104:105], v[104:105], v[214:215]
	s_waitcnt lgkmcnt(0)
	v_pk_add_f32 v[100:101], v[100:101], v[220:221]
	v_pk_add_f32 v[98:99], v[98:99], v[218:219]
	ds_read_b128 v[190:193], v103 offset:32768
	ds_read_b128 v[194:197], v103 offset:33792
	ds_read_b128 v[198:201], v103 offset:34816
	ds_read_b128 v[202:205], v103 offset:35840
	ds_read_b128 v[206:209], v103 offset:36864
	ds_read_b128 v[210:213], v103 offset:37888
	ds_read_b128 v[214:217], v103 offset:38912
	ds_read_b128 v[218:221], v103 offset:39936
	s_waitcnt lgkmcnt(7)
	v_pk_add_f32 v[94:95], v[94:95], v[190:191]
	v_pk_add_f32 v[96:97], v[96:97], v[192:193]
	s_waitcnt lgkmcnt(6)
	v_pk_add_f32 v[90:91], v[90:91], v[194:195]
	v_pk_add_f32 v[92:93], v[92:93], v[196:197]
	s_waitcnt lgkmcnt(5)
	v_pk_add_f32 v[86:87], v[86:87], v[198:199]
	v_pk_add_f32 v[88:89], v[88:89], v[200:201]
	s_waitcnt lgkmcnt(4)
	v_pk_add_f32 v[82:83], v[82:83], v[202:203]
	v_pk_add_f32 v[84:85], v[84:85], v[204:205]
	s_waitcnt lgkmcnt(3)
	v_pk_add_f32 v[78:79], v[78:79], v[206:207]
	v_pk_add_f32 v[80:81], v[80:81], v[208:209]
	s_waitcnt lgkmcnt(2)
	v_pk_add_f32 v[74:75], v[74:75], v[210:211]
	v_pk_add_f32 v[76:77], v[76:77], v[212:213]
	s_waitcnt lgkmcnt(1)
	v_pk_add_f32 v[104:105], v[104:105], v[214:215]
	v_pk_add_f32 v[106:107], v[106:107], v[216:217]
	s_waitcnt lgkmcnt(0)
	v_pk_add_f32 v[98:99], v[98:99], v[218:219]
	v_pk_add_f32 v[100:101], v[100:101], v[220:221]
	ds_read_b128 v[190:193], v103 offset:40960
	ds_read_b128 v[194:197], v103 offset:41984
	ds_read_b128 v[198:201], v103 offset:43008
	ds_read_b128 v[202:205], v103 offset:44032
	ds_read_b128 v[206:209], v103 offset:45056
	ds_read_b128 v[210:213], v103 offset:46080
	ds_read_b128 v[214:217], v103 offset:47104
	ds_read_b128 v[218:221], v103 offset:48128
	s_waitcnt lgkmcnt(7)
	v_pk_add_f32 v[96:97], v[96:97], v[192:193]
	v_pk_add_f32 v[94:95], v[94:95], v[190:191]
	s_waitcnt lgkmcnt(6)
	v_pk_add_f32 v[92:93], v[92:93], v[196:197]
	v_pk_add_f32 v[90:91], v[90:91], v[194:195]
	s_waitcnt lgkmcnt(5)
	v_pk_add_f32 v[88:89], v[88:89], v[200:201]
	v_pk_add_f32 v[86:87], v[86:87], v[198:199]
	s_waitcnt lgkmcnt(4)
	v_pk_add_f32 v[84:85], v[84:85], v[204:205]
	v_pk_add_f32 v[82:83], v[82:83], v[202:203]
	s_waitcnt lgkmcnt(3)
	v_pk_add_f32 v[80:81], v[80:81], v[208:209]
	v_pk_add_f32 v[78:79], v[78:79], v[206:207]
	s_waitcnt lgkmcnt(2)
	v_pk_add_f32 v[76:77], v[76:77], v[212:213]
	v_pk_add_f32 v[74:75], v[74:75], v[210:211]
	s_waitcnt lgkmcnt(1)
	v_pk_add_f32 v[106:107], v[106:107], v[216:217]
	v_pk_add_f32 v[104:105], v[104:105], v[214:215]
	s_waitcnt lgkmcnt(0)
	v_pk_add_f32 v[100:101], v[100:101], v[220:221]
	v_pk_add_f32 v[98:99], v[98:99], v[218:219]
	ds_read_b128 v[190:193], v103 offset:49152
	ds_read_b128 v[194:197], v103 offset:50176
	ds_read_b128 v[198:201], v103 offset:51200
	ds_read_b128 v[202:205], v103 offset:52224
	ds_read_b128 v[206:209], v103 offset:53248
	s_waitcnt lgkmcnt(4)
	v_pk_add_f32 v[94:95], v[94:95], v[190:191]
	v_pk_add_f32 v[96:97], v[96:97], v[192:193]
	s_waitcnt lgkmcnt(3)
	v_pk_add_f32 v[90:91], v[90:91], v[194:195]
	v_pk_add_f32 v[92:93], v[92:93], v[196:197]
	s_waitcnt lgkmcnt(2)
	v_pk_add_f32 v[86:87], v[86:87], v[198:199]
	v_pk_add_f32 v[88:89], v[88:89], v[200:201]
	s_waitcnt lgkmcnt(1)
	v_pk_add_f32 v[108:109], v[82:83], v[202:203]
	v_pk_add_f32 v[110:111], v[84:85], v[204:205]
	s_waitcnt lgkmcnt(0)
	v_pk_add_f32 v[112:113], v[78:79], v[206:207]
	v_pk_add_f32 v[114:115], v[80:81], v[208:209]
	ds_read_b128 v[70:73], v103 offset:54272
	ds_read_b128 v[80:83], v103 offset:59392
	s_waitcnt lgkmcnt(1)
; #define LAS __attribute__((address_space(3)))
; __device__ __forceinline__ void ln_phase(const bf16_t* Z, const bf16_t* RES, const float* part, int nsl, const float* g, const float* b, bf16_t* XB, float* outp, float* outs, int gw, int NGW, int lane,
;                                          LAS float* scr, int wave, int bid, int nblk) {
;     ...
;             for (int w8 = 0; w8 < 8; ++w8)
; #pragma unroll
;                 for (int j = 0; j < 8; ++j) v[j] += *(LAS const f32x4*)(scr + w8 * 2048 + (lane + 64 * j) * 4);
	v_pk_add_f32 v[116:117], v[74:75], v[70:71]
	v_pk_add_f32 v[118:119], v[76:77], v[72:73]
	ds_read_b128 v[70:73], v103 offset:55296
	ds_read_b128 v[76:79], v103 offset:58368
	s_waitcnt lgkmcnt(2)
	v_pk_add_f32 v[80:81], v[86:87], v[80:81]
	ds_read_b128 v[84:87], v103 offset:60416
	s_waitcnt lgkmcnt(2)
	v_pk_add_f32 v[104:105], v[104:105], v[70:71]
	v_pk_add_f32 v[106:107], v[106:107], v[72:73]
	ds_read_b128 v[70:73], v103 offset:56320
	s_waitcnt lgkmcnt(2)
	v_pk_add_f32 v[76:77], v[90:91], v[76:77]
	s_waitcnt lgkmcnt(1)
	v_pk_add_f32 v[84:85], v[108:109], v[84:85]
	s_waitcnt lgkmcnt(0)
	v_pk_add_f32 v[100:101], v[100:101], v[72:73]
	ds_read_b128 v[72:75], v103 offset:57344
	v_pk_add_f32 v[120:121], v[98:99], v[70:71]
	s_waitcnt lgkmcnt(0)
	v_pk_add_f32 v[70:71], v[96:97], v[74:75]
	v_pk_add_f32 v[72:73], v[94:95], v[72:73]
	v_pk_add_f32 v[74:75], v[92:93], v[78:79]
	v_pk_add_f32 v[78:79], v[88:89], v[82:83]
	ds_read_b128 v[88:91], v103 offset:61440
	ds_read_b128 v[92:95], v103 offset:62464
	ds_read_b128 v[96:99], v103 offset:63488
	v_pk_add_f32 v[82:83], v[110:111], v[86:87]
	v_mov_b32_e32 v108, v71
	s_waitcnt lgkmcnt(2)
	v_pk_add_f32 v[86:87], v[114:115], v[90:91]
	s_waitcnt lgkmcnt(1)
	v_pk_add_f32 v[90:91], v[118:119], v[94:95]
	s_waitcnt lgkmcnt(0)
	v_pk_add_f32 v[94:95], v[106:107], v[98:99]
	v_pk_add_f32 v[96:97], v[104:105], v[96:97]
	ds_read_b128 v[104:107], v103 offset:64512
	v_mov_b32_e32 v109, v75
	v_pk_add_f32 v[88:89], v[112:113], v[88:89]
	v_add_f32_e32 v110, v82, v83
	v_mov_b32_e32 v111, v87
	s_waitcnt lgkmcnt(0)
	v_pk_add_f32 v[98:99], v[100:101], v[106:107]
	v_pk_add_f32 v[100:101], v[120:121], v[104:105]
	v_mov_b32_e32 v104, v72
	v_mov_b32_e32 v105, v76
	v_mov_b32_e32 v106, v73
	v_mov_b32_e32 v107, v77
	v_pk_add_f32 v[104:105], v[104:105], v[106:107]
	v_mov_b32_e32 v106, v70
	v_mov_b32_e32 v107, v74
	v_pk_add_f32 v[106:107], v[106:107], v[108:109]
	v_mov_b32_e32 v108, v80
	v_pk_add_f32 v[104:105], v[104:105], v[106:107]
	v_pk_mov_b32 v[106:107], v[80:81], v[78:79] op_sel:[1,0]
	v_mov_b32_e32 v109, v79
	v_pk_add_f32 v[106:107], v[106:107], v[108:109]
	v_add_f32_e32 v104, 0, v104
	v_pk_add_f32 v[106:107], v[106:107], v[106:107] op_sel:[0,1] op_sel_hi:[1,0]
	v_add_f32_e32 v104, v104, v105
	v_add_f32_e32 v108, v84, v85
	v_mov_b32_e32 v105, v88
	v_mov_b32_e32 v107, v89
	v_mov_b32_e32 v109, v86
	v_pk_add_f32 v[92:93], v[116:117], v[92:93]
	v_pk_add_f32 v[104:105], v[104:105], v[106:107]
	v_pk_add_f32 v[106:107], v[108:109], v[110:111]
	v_mov_b32_e32 v108, v92
	v_pk_add_f32 v[104:105], v[104:105], v[106:107]
	v_pk_mov_b32 v[106:107], v[92:93], v[90:91] op_sel:[1,0]
	v_mov_b32_e32 v109, v91
	v_pk_add_f32 v[106:107], v[106:107], v[108:109]
	v_pk_add_f32 v[104:105], v[104:105], v[104:105] op_sel:[0,1] op_sel_hi:[1,0]
	v_pk_add_f32 v[106:107], v[106:107], v[106:107] op_sel:[0,1] op_sel_hi:[1,0]
	v_add_f32_e32 v108, v96, v97
	v_add_f32_e32 v110, v94, v95
	v_mov_b32_e32 v105, v100
	v_mov_b32_e32 v107, v101
	v_mov_b32_e32 v109, v98
	v_mov_b32_e32 v111, v99
	v_pk_add_f32 v[104:105], v[104:105], v[106:107]
	v_pk_add_f32 v[106:107], v[108:109], v[110:111]
	s_nop 0
	v_pk_add_f32 v[104:105], v[104:105], v[106:107]
	v_xor_b32_e32 v106, 1, v185
	v_add_f32_e32 v104, v104, v105
	v_and_b32_e32 v105, 64, v185
	v_add_u32_e32 v105, 64, v105
	v_cmp_lt_i32_e32 vcc, v106, v105
	s_nop 1
	v_cndmask_b32_e32 v106, v185, v106, vcc
	v_lshlrev_b32_e32 v112, 2, v106
	ds_bpermute_b32 v106, v112, v104
	s_waitcnt lgkmcnt(0)
	v_add_f32_e32 v104, v104, v106
	v_xor_b32_e32 v106, 2, v185
	v_cmp_lt_i32_e32 vcc, v106, v105
	s_nop 1
	v_cndmask_b32_e32 v106, v185, v106, vcc
	v_lshlrev_b32_e32 v113, 2, v106
	ds_bpermute_b32 v106, v113, v104
	s_waitcnt lgkmcnt(0)
	v_add_f32_e32 v104, v104, v106
	v_xor_b32_e32 v106, 4, v185
	v_cmp_lt_i32_e32 vcc, v106, v105
	s_nop 1
	v_cndmask_b32_e32 v106, v185, v106, vcc
	v_lshlrev_b32_e32 v114, 2, v106
	ds_bpermute_b32 v106, v114, v104
	s_waitcnt lgkmcnt(0)
	v_add_f32_e32 v104, v104, v106
	v_xor_b32_e32 v106, 8, v185
	v_cmp_lt_i32_e32 vcc, v106, v105
	s_nop 1
	v_cndmask_b32_e32 v106, v185, v106, vcc
	v_lshlrev_b32_e32 v115, 2, v106
	ds_bpermute_b32 v106, v115, v104
	s_waitcnt lgkmcnt(0)
	v_add_f32_e32 v104, v104, v106
	v_xor_b32_e32 v106, 16, v185
	v_cmp_lt_i32_e32 vcc, v106, v105
	s_nop 1
	v_cndmask_b32_e32 v106, v185, v106, vcc
	v_lshlrev_b32_e32 v116, 2, v106
	ds_bpermute_b32 v106, v116, v104
	s_waitcnt lgkmcnt(0)
	v_add_f32_e32 v104, v104, v106
	v_xor_b32_e32 v106, 32, v185
	v_cmp_lt_i32_e32 vcc, v106, v105
	s_nop 1
	v_cndmask_b32_e32 v105, v185, v106, vcc
	v_lshlrev_b32_e32 v117, 2, v105
	ds_bpermute_b32 v105, v117, v104
	s_waitcnt lgkmcnt(0)
	v_add_f32_e32 v118, v104, v105
	v_fmamk_f32 v73, v118, 0xba000000, v73
	v_fmamk_f32 v77, v118, 0xba000000, v77
	v_fmamk_f32 v71, v118, 0xba000000, v71
	v_fmac_f32_e32 v72, 0xba000000, v118
	v_fmamk_f32 v75, v118, 0xba000000, v75
	v_fmac_f32_e32 v76, 0xba000000, v118
	v_mov_b32_e32 v106, v73
	v_mov_b32_e32 v107, v77
	v_fmac_f32_e32 v70, 0xba000000, v118
	v_fmac_f32_e32 v74, 0xba000000, v118
	v_mov_b32_e32 v104, v72
	v_mov_b32_e32 v105, v76
	v_pk_mul_f32 v[106:107], v[106:107], v[106:107]
	v_mov_b32_e32 v108, v71
	v_mov_b32_e32 v109, v75
	v_pk_fma_f32 v[104:105], v[104:105], v[104:105], v[106:107]
	v_mov_b32_e32 v106, v70
	v_mov_b32_e32 v107, v74
	v_pk_mul_f32 v[108:109], v[108:109], v[108:109]
	v_fmamk_f32 v81, v118, 0xba000000, v81
	v_pk_fma_f32 v[106:107], v[106:107], v[106:107], v[108:109]
	v_fmac_f32_e32 v80, 0xba000000, v118
	v_pk_add_f32 v[104:105], v[104:105], v[106:107]
	v_fmamk_f32 v79, v118, 0xba000000, v79
	v_fmac_f32_e32 v78, 0xba000000, v118
	v_pk_add_f32 v[104:105], v[104:105], v[104:105] op_sel_hi:[0,1]
	v_pk_mul_f32 v[106:107], v[78:79], v[78:79]
	v_pk_mul_f32 v[108:109], v[80:81], v[80:81]
	v_fmac_f32_e32 v84, 0xba000000, v118
	v_pk_mov_b32 v[110:111], v[108:109], v[106:107] op_sel:[1,0]
	v_mov_b32_e32 v109, v107
	v_fmamk_f32 v85, v118, 0xba000000, v85
	v_fmac_f32_e32 v82, 0xba000000, v118
	v_mul_f32_e32 v104, v84, v84
	v_pk_add_f32 v[106:107], v[110:111], v[108:109]
	v_fmamk_f32 v83, v118, 0xba000000, v83
	v_pk_fma_f32 v[108:109], v[84:85], v[84:85], v[104:105] op_sel_hi:[1,1,0]
	v_mul_f32_e32 v104, v82, v82
	v_pk_add_f32 v[106:107], v[106:107], v[106:107] op_sel_hi:[0,1]
	v_pk_fma_f32 v[110:111], v[82:83], v[82:83], v[104:105] op_sel_hi:[1,1,0]
	v_fmamk_f32 v87, v118, 0xba000000, v87
	v_fmac_f32_e32 v86, 0xba000000, v118
	v_fmamk_f32 v89, v118, 0xba000000, v89
	v_fmac_f32_e32 v88, 0xba000000, v118
	v_mul_f32_e32 v108, v88, v88
	v_mul_f32_e32 v110, v89, v89
	v_mul_f32_e32 v106, v86, v86
	v_mul_f32_e32 v104, v87, v87
	v_pk_add_f32 v[108:109], v[108:109], v[110:111]
	v_pk_add_f32 v[104:105], v[106:107], v[104:105]
	v_fmamk_f32 v93, v118, 0xba000000, v93
	v_pk_add_f32 v[104:105], v[108:109], v[104:105]
	v_fmac_f32_e32 v92, 0xba000000, v118
	v_fmamk_f32 v91, v118, 0xba000000, v91
	v_fmac_f32_e32 v90, 0xba000000, v118
	v_pk_add_f32 v[104:105], v[104:105], v[104:105] op_sel_hi:[0,1]
	v_pk_mul_f32 v[106:107], v[90:91], v[90:91]
	v_pk_mul_f32 v[108:109], v[92:93], v[92:93]
	v_fmac_f32_e32 v96, 0xba000000, v118
	v_pk_mov_b32 v[110:111], v[108:109], v[106:107] op_sel:[1,0]
	v_mov_b32_e32 v109, v107
	v_fmamk_f32 v97, v118, 0xba000000, v97
	v_fmac_f32_e32 v94, 0xba000000, v118
	v_mul_f32_e32 v104, v96, v96
	v_pk_add_f32 v[106:107], v[110:111], v[108:109]
	v_fmamk_f32 v95, v118, 0xba000000, v95
	v_pk_fma_f32 v[108:109], v[96:97], v[96:97], v[104:105] op_sel_hi:[1,1,0]
	v_mul_f32_e32 v104, v94, v94
	v_pk_add_f32 v[106:107], v[106:107], v[106:107] op_sel_hi:[0,1]
	v_pk_fma_f32 v[110:111], v[94:95], v[94:95], v[104:105] op_sel_hi:[1,1,0]
	v_fmamk_f32 v99, v118, 0xba000000, v99
	v_fmac_f32_e32 v98, 0xba000000, v118
	v_fmamk_f32 v101, v118, 0xba000000, v101
	v_fmac_f32_e32 v100, 0xba000000, v118
	v_mul_f32_e32 v108, v100, v100
	v_mul_f32_e32 v110, v101, v101
	v_mul_f32_e32 v106, v98, v98
	v_mul_f32_e32 v104, v99, v99
	v_pk_add_f32 v[108:109], v[108:109], v[110:111]
	v_pk_add_f32 v[104:105], v[106:107], v[104:105]
	s_nop 0
	v_pk_add_f32 v[104:105], v[108:109], v[104:105]
	s_nop 0
	v_add_f32_e32 v104, v104, v105
	ds_bpermute_b32 v105, v112, v104
	s_waitcnt lgkmcnt(0)
	v_add_f32_e32 v104, v104, v105
	ds_bpermute_b32 v105, v113, v104
	s_waitcnt lgkmcnt(0)
	v_add_f32_e32 v104, v104, v105
	ds_bpermute_b32 v105, v114, v104
	s_waitcnt lgkmcnt(0)
	v_add_f32_e32 v104, v104, v105
	ds_bpermute_b32 v105, v115, v104
	s_waitcnt lgkmcnt(0)
	v_add_f32_e32 v104, v104, v105
	ds_bpermute_b32 v105, v116, v104
	s_waitcnt lgkmcnt(0)
	v_add_f32_e32 v104, v104, v105
	ds_bpermute_b32 v105, v117, v104
	s_waitcnt lgkmcnt(0)
	v_add_f32_e32 v104, v104, v105
	v_fmamk_f32 v104, v104, 0x3a000000, v181
	v_cmp_gt_f32_e32 vcc, s65, v104
	v_mul_f32_e32 v105, 0x4f800000, v104
	s_nop 0
	v_cndmask_b32_e32 v104, v104, v105, vcc
	v_sqrt_f32_e32 v105, v104
	s_nop 0
	v_add_u32_e32 v106, -1, v105
	v_fma_f32 v107, -v106, v105, v104
	v_cmp_ge_f32_e64 s[0:1], 0, v107
	v_add_u32_e32 v107, 1, v105
	s_nop 0
	v_cndmask_b32_e64 v106, v105, v106, s[0:1]
	v_fma_f32 v105, -v107, v105, v104
	v_cmp_lt_f32_e64 s[0:1], 0, v105
	s_nop 1
	v_cndmask_b32_e64 v105, v106, v107, s[0:1]
	v_mul_f32_e32 v106, 0x37800000, v105
	v_cndmask_b32_e32 v105, v105, v106, vcc
	v_cmp_class_f32_e32 vcc, v104, v182
	s_nop 1
	v_cndmask_b32_e32 v104, v105, v104, vcc
	v_div_scale_f32 v105, s[0:1], v104, v104, 1.0
	v_rcp_f32_e32 v106, v105
	s_nop 0
	v_fma_f32 v107, -v105, v106, 1.0
	v_fmac_f32_e32 v106, v107, v106
	v_div_scale_f32 v107, vcc, 1.0, v104, 1.0
	v_mul_f32_e32 v108, v107, v106
	v_fma_f32 v109, -v105, v108, v107
	v_fmac_f32_e32 v108, v109, v106
	v_fma_f32 v105, -v105, v108, v107
	v_div_fmas_f32 v105, v105, v106, v108
	v_div_fixup_f32 v104, v105, v104, 1.0
	v_pk_mul_f32 v[72:73], v[72:73], v[104:105] op_sel_hi:[1,0]
	v_pk_mul_f32 v[70:71], v[70:71], v[104:105] op_sel_hi:[1,0]
	v_pk_fma_f32 v[72:73], v[2:3], v[72:73], v[10:11]
	v_pk_fma_f32 v[70:71], v[4:5], v[70:71], v[12:13]
	v_pk_mul_f32 v[76:77], v[76:77], v[104:105] op_sel_hi:[1,0]
	v_pk_mul_f32 v[74:75], v[74:75], v[104:105] op_sel_hi:[1,0]
	v_pk_fma_f32 v[76:77], v[6:7], v[76:77], v[14:15]
	v_pk_fma_f32 v[74:75], v[8:9], v[74:75], v[16:17]
	v_pk_mul_f32 v[80:81], v[80:81], v[104:105] op_sel_hi:[1,0]
	v_pk_mul_f32 v[78:79], v[78:79], v[104:105] op_sel_hi:[1,0]
	v_cvt_pk_bf16_f32 v72, v72, v73
	v_cvt_pk_bf16_f32 v73, v70, v71
	v_pk_fma_f32 v[78:79], v[20:21], v[78:79], v[28:29]
	v_pk_fma_f32 v[80:81], v[18:19], v[80:81], v[26:27]
	v_pk_mul_f32 v[84:85], v[84:85], v[104:105] op_sel_hi:[1,0]
	v_pk_mul_f32 v[82:83], v[82:83], v[104:105] op_sel_hi:[1,0]
	global_store_dwordx2 v[68:69], v[72:73], off
	v_cvt_pk_bf16_f32 v68, v76, v77
	v_cvt_pk_bf16_f32 v69, v74, v75
	v_pk_fma_f32 v[82:83], v[24:25], v[82:83], v[32:33]
	v_pk_fma_f32 v[84:85], v[22:23], v[84:85], v[30:31]
	v_pk_mul_f32 v[88:89], v[88:89], v[104:105] op_sel_hi:[1,0]
	v_pk_mul_f32 v[86:87], v[86:87], v[104:105] op_sel_hi:[1,0]
	global_store_dwordx2 v[66:67], v[68:69], off offset:512
	v_cvt_pk_bf16_f32 v68, v80, v81
	v_cvt_pk_bf16_f32 v69, v78, v79
	v_pk_fma_f32 v[86:87], v[36:37], v[86:87], v[40:41]
	v_pk_fma_f32 v[88:89], v[34:35], v[88:89], v[38:39]
	v_pk_mul_f32 v[92:93], v[92:93], v[104:105] op_sel_hi:[1,0]
	v_pk_mul_f32 v[90:91], v[90:91], v[104:105] op_sel_hi:[1,0]
	global_store_dwordx2 v[66:67], v[68:69], off offset:1024
	v_cvt_pk_bf16_f32 v68, v84, v85
	v_cvt_pk_bf16_f32 v69, v82, v83
	v_pk_fma_f32 v[90:91], v[44:45], v[90:91], v[48:49]
	v_pk_fma_f32 v[92:93], v[42:43], v[92:93], v[46:47]
	v_pk_mul_f32 v[96:97], v[96:97], v[104:105] op_sel_hi:[1,0]
	v_pk_mul_f32 v[94:95], v[94:95], v[104:105] op_sel_hi:[1,0]
	global_store_dwordx2 v[66:67], v[68:69], off offset:1536
	v_cvt_pk_bf16_f32 v68, v88, v89
	v_cvt_pk_bf16_f32 v69, v86, v87
	v_pk_fma_f32 v[94:95], v[52:53], v[94:95], v[56:57]
	v_pk_fma_f32 v[96:97], v[50:51], v[96:97], v[54:55]
	v_pk_mul_f32 v[100:101], v[100:101], v[104:105] op_sel_hi:[1,0]
	v_pk_mul_f32 v[98:99], v[98:99], v[104:105] op_sel_hi:[1,0]
	global_store_dwordx2 v[66:67], v[68:69], off offset:2048
	v_cvt_pk_bf16_f32 v68, v92, v93
	v_cvt_pk_bf16_f32 v69, v90, v91
	v_pk_fma_f32 v[98:99], v[60:61], v[98:99], v[64:65]
	v_pk_fma_f32 v[100:101], v[58:59], v[100:101], v[62:63]
	global_store_dwordx2 v[66:67], v[68:69], off offset:2560
	v_cvt_pk_bf16_f32 v68, v96, v97
	v_cvt_pk_bf16_f32 v69, v94, v95
	global_store_dwordx2 v[66:67], v[68:69], off offset:3072
	v_cvt_pk_bf16_f32 v68, v100, v101
	v_cvt_pk_bf16_f32 v69, v98, v99
	global_store_dwordx2 v[66:67], v[68:69], off offset:3584
	s_branch .LBB0_123

; #define LAS __attribute__((address_space(3)))
; #define GAS __attribute__((address_space(1)))
; __device__ __forceinline__ float bflo(unsigned u) { return __uint_as_float(u << 16); }
; __device__ __forceinline__ float bfhi(unsigned u) { return __uint_as_float(u & 0xffff0000u); }
; __device__ __forceinline__ void ln_phase(const bf16_t* Z, const bf16_t* RES, const float* part, int nsl, const float* g, const float* b, bf16_t* XB, float* outp, float* outs, int gw, int NGW, int lane,
;                                          LAS float* scr, int wave, int bid, int nblk) {
;     ...
;             for (int j = 0; j < 8; ++j) acc[j] += p[64 * j]; }
; #pragma unroll
;         for (int j = 0; j < 8; ++j) *(LAS f32x4*)(scr + wave * 2048 + (lane + 64 * j) * 4) = acc[j];
;         __syncthreads();
;         if (wave == 0) { const GAS u32x2* z_ = (const GAS u32x2*)(RES + (size_t)(MP + r) * DM) + lane; f32x4 v[8];
; #pragma unroll
;             for (int j = 0; j < 8; ++j) { const u32x2 w = z_[64 * j]; v[j] = (f32x4){ALPHA * bflo(w.x), ALPHA * bfhi(w.x), ALPHA * bflo(w.y), ALPHA * bfhi(w.y)}; }
; #pragma unroll
;             for (int w8 = 0; w8 < 8; ++w8)
; #pragma unroll
;                 for (int j = 0; j < 8; ++j) v[j] += *(LAS const f32x4*)(scr + w8 * 2048 + (lane + 64 * j) * 4);
.LBB0_915:
	v_add_u32_e32 v100, s67, v0
	s_and_b64 vcc, exec, s[80:81]
	ds_write_b128 v100, v[90:93]
	ds_write_b128 v100, v[94:97] offset:1024
	ds_write_b128 v100, v[86:89] offset:2048
	ds_write_b128 v100, v[82:85] offset:3072
	ds_write_b128 v100, v[78:81] offset:4096
	ds_write_b128 v100, v[74:77] offset:5120
	ds_write_b128 v100, v[70:73] offset:6144
	ds_write_b128 v100, v[66:69] offset:7168
	s_waitcnt lgkmcnt(0)
	s_barrier
	s_cbranch_vccz .LBB0_911
	s_add_i32 s44, s2, 0x4000
	s_ashr_i32 s45, s44, 31
	s_lshl_b64 s[0:1], s[44:45], 12
	s_add_u32 s0, s30, s0
	s_addc_u32 s1, s31, s1
	v_lshlrev_b32_e32 v68, 3, v98
	global_load_dwordx2 v[222:223], v68, s[0:1]
	global_load_dwordx2 v[224:225], v68, s[0:1] offset:512
	global_load_dwordx2 v[226:227], v68, s[0:1] offset:1024
	global_load_dwordx2 v[228:229], v68, s[0:1] offset:1536
	global_load_dwordx2 v[142:143], v68, s[0:1] offset:2048
	global_load_dwordx2 v[144:145], v68, s[0:1] offset:2560
	global_load_dwordx2 v[146:147], v68, s[0:1] offset:3072
	global_load_dwordx2 v[148:149], v68, s[0:1] offset:3584
	s_waitcnt vmcnt(0)
	v_lshlrev_b32_e32 v70, 16, v222
	v_and_b32_e32 v71, 0xffff0000, v222
	v_lshlrev_b32_e32 v72, 16, v223
	v_and_b32_e32 v73, 0xffff0000, v223
	v_lshlrev_b32_e32 v74, 16, v224
	v_and_b32_e32 v75, 0xffff0000, v224
	v_lshlrev_b32_e32 v76, 16, v225
	v_and_b32_e32 v77, 0xffff0000, v225
	v_lshlrev_b32_e32 v78, 16, v226
	v_and_b32_e32 v79, 0xffff0000, v226
	v_lshlrev_b32_e32 v80, 16, v227
	v_and_b32_e32 v81, 0xffff0000, v227
	v_lshlrev_b32_e32 v82, 16, v228
	v_and_b32_e32 v83, 0xffff0000, v228
	v_lshlrev_b32_e32 v84, 16, v229
	v_and_b32_e32 v85, 0xffff0000, v229
	v_lshlrev_b32_e32 v86, 16, v142
	v_and_b32_e32 v87, 0xffff0000, v142
	v_lshlrev_b32_e32 v88, 16, v143
	v_and_b32_e32 v89, 0xffff0000, v143
	v_lshlrev_b32_e32 v90, 16, v144
	v_and_b32_e32 v91, 0xffff0000, v144
	v_lshlrev_b32_e32 v92, 16, v145
	v_and_b32_e32 v93, 0xffff0000, v145
	v_lshlrev_b32_e32 v94, 16, v146
	v_and_b32_e32 v95, 0xffff0000, v146
	v_lshlrev_b32_e32 v96, 16, v147
	v_and_b32_e32 v97, 0xffff0000, v147
	v_lshlrev_b32_e32 v100, 16, v148
	v_and_b32_e32 v101, 0xffff0000, v148
	v_lshlrev_b32_e32 v102, 16, v149
	v_and_b32_e32 v103, 0xffff0000, v149
	ds_read_b128 v[190:193], v99
	ds_read_b128 v[194:197], v99 offset:1024
	ds_read_b128 v[198:201], v99 offset:2048
	ds_read_b128 v[202:205], v99 offset:3072
	ds_read_b128 v[206:209], v99 offset:4096
	ds_read_b128 v[210:213], v99 offset:5120
	ds_read_b128 v[214:217], v99 offset:6144
	ds_read_b128 v[218:221], v99 offset:7168
	s_waitcnt lgkmcnt(7)
	v_pk_fma_f32 v[70:71], v[70:71], s[52:53], v[190:191] op_sel_hi:[1, 0, 1]
	v_pk_fma_f32 v[72:73], v[72:73], s[52:53], v[192:193] op_sel_hi:[1, 0, 1]
	s_waitcnt lgkmcnt(6)
	v_pk_fma_f32 v[74:75], v[74:75], s[52:53], v[194:195] op_sel_hi:[1, 0, 1]
	v_pk_fma_f32 v[76:77], v[76:77], s[52:53], v[196:197] op_sel_hi:[1, 0, 1]
	s_waitcnt lgkmcnt(5)
	v_pk_fma_f32 v[78:79], v[78:79], s[52:53], v[198:199] op_sel_hi:[1, 0, 1]
	v_pk_fma_f32 v[80:81], v[80:81], s[52:53], v[200:201] op_sel_hi:[1, 0, 1]
	s_waitcnt lgkmcnt(4)
	v_pk_fma_f32 v[104:105], v[82:83], s[52:53], v[202:203] op_sel_hi:[1, 0, 1]
	v_pk_fma_f32 v[106:107], v[84:85], s[52:53], v[204:205] op_sel_hi:[1, 0, 1]
	s_waitcnt lgkmcnt(3)
	v_pk_fma_f32 v[108:109], v[86:87], s[52:53], v[206:207] op_sel_hi:[1, 0, 1]
	v_pk_fma_f32 v[110:111], v[88:89], s[52:53], v[208:209] op_sel_hi:[1, 0, 1]
	s_waitcnt lgkmcnt(2)
	v_pk_fma_f32 v[112:113], v[90:91], s[52:53], v[210:211] op_sel_hi:[1, 0, 1]
	v_pk_fma_f32 v[114:115], v[92:93], s[52:53], v[212:213] op_sel_hi:[1, 0, 1]
	s_waitcnt lgkmcnt(1)
	v_pk_fma_f32 v[116:117], v[94:95], s[52:53], v[214:215] op_sel_hi:[1, 0, 1]
	v_pk_fma_f32 v[118:119], v[96:97], s[52:53], v[216:217] op_sel_hi:[1, 0, 1]
	s_waitcnt lgkmcnt(0)
	v_pk_fma_f32 v[94:95], v[100:101], s[52:53], v[218:219] op_sel_hi:[1, 0, 1]
	v_pk_fma_f32 v[96:97], v[102:103], s[52:53], v[220:221] op_sel_hi:[1, 0, 1]
	ds_read_b128 v[190:193], v99 offset:8192
	ds_read_b128 v[194:197], v99 offset:14336
	ds_read_b128 v[198:201], v99 offset:9216
	ds_read_b128 v[202:205], v99 offset:10240
	ds_read_b128 v[206:209], v99 offset:11264
	ds_read_b128 v[210:213], v99 offset:12288
	ds_read_b128 v[214:217], v99 offset:13312
	ds_read_b128 v[218:221], v99 offset:15360
	s_waitcnt lgkmcnt(7)
	v_pk_add_f32 v[90:91], v[72:73], v[192:193]
	v_pk_add_f32 v[92:93], v[70:71], v[190:191]
	s_waitcnt lgkmcnt(5)
	v_pk_add_f32 v[86:87], v[76:77], v[200:201]
	v_pk_add_f32 v[88:89], v[74:75], v[198:199]
	s_waitcnt lgkmcnt(4)
	v_pk_add_f32 v[82:83], v[80:81], v[204:205]
	v_pk_add_f32 v[84:85], v[78:79], v[202:203]
	s_waitcnt lgkmcnt(3)
	v_pk_add_f32 v[78:79], v[106:107], v[208:209]
	v_pk_add_f32 v[80:81], v[104:105], v[206:207]
	s_waitcnt lgkmcnt(2)
	v_pk_add_f32 v[74:75], v[110:111], v[212:213]
	v_pk_add_f32 v[76:77], v[108:109], v[210:211]
	s_waitcnt lgkmcnt(1)
	v_pk_add_f32 v[70:71], v[114:115], v[216:217]
	v_pk_add_f32 v[72:73], v[112:113], v[214:215]
	v_pk_add_f32 v[66:67], v[118:119], v[196:197]
	v_pk_add_f32 v[68:69], v[116:117], v[194:195]
	s_waitcnt lgkmcnt(0)
	v_pk_add_f32 v[102:103], v[96:97], v[220:221]
	v_pk_add_f32 v[100:101], v[94:95], v[218:219]
	ds_read_b128 v[190:193], v99 offset:16384
	ds_read_b128 v[194:197], v99 offset:17408
	ds_read_b128 v[198:201], v99 offset:18432
	ds_read_b128 v[202:205], v99 offset:19456
	ds_read_b128 v[206:209], v99 offset:20480
	ds_read_b128 v[210:213], v99 offset:21504
	ds_read_b128 v[214:217], v99 offset:22528
	ds_read_b128 v[218:221], v99 offset:23552
	s_waitcnt lgkmcnt(7)
	v_pk_add_f32 v[94:95], v[92:93], v[190:191]
	v_pk_add_f32 v[96:97], v[90:91], v[192:193]
	s_waitcnt lgkmcnt(6)
; #define LAS __attribute__((address_space(3)))
; __device__ __forceinline__ void ln_phase(const bf16_t* Z, const bf16_t* RES, const float* part, int nsl, const float* g, const float* b, bf16_t* XB, float* outp, float* outs, int gw, int NGW, int lane,
;                                          LAS float* scr, int wave, int bid, int nblk) {
;     ...
;             for (int w8 = 0; w8 < 8; ++w8)
; #pragma unroll
;                 for (int j = 0; j < 8; ++j) v[j] += *(LAS const f32x4*)(scr + w8 * 2048 + (lane + 64 * j) * 4);
	v_pk_add_f32 v[90:91], v[88:89], v[194:195]
	v_pk_add_f32 v[92:93], v[86:87], v[196:197]
	s_waitcnt lgkmcnt(5)
	v_pk_add_f32 v[86:87], v[84:85], v[198:199]
	v_pk_add_f32 v[88:89], v[82:83], v[200:201]
	s_waitcnt lgkmcnt(4)
	v_pk_add_f32 v[82:83], v[80:81], v[202:203]
	v_pk_add_f32 v[84:85], v[78:79], v[204:205]
	s_waitcnt lgkmcnt(3)
	v_pk_add_f32 v[78:79], v[76:77], v[206:207]
	v_pk_add_f32 v[80:81], v[74:75], v[208:209]
	s_waitcnt lgkmcnt(2)
	v_pk_add_f32 v[74:75], v[72:73], v[210:211]
	v_pk_add_f32 v[76:77], v[70:71], v[212:213]
	s_waitcnt lgkmcnt(1)
	v_pk_add_f32 v[70:71], v[68:69], v[214:215]
	v_pk_add_f32 v[72:73], v[66:67], v[216:217]
	s_waitcnt lgkmcnt(0)
	v_pk_add_f32 v[100:101], v[100:101], v[218:219]
	v_pk_add_f32 v[102:103], v[102:103], v[220:221]
	ds_read_b128 v[190:193], v99 offset:24576
	ds_read_b128 v[194:197], v99 offset:25600
	ds_read_b128 v[198:201], v99 offset:26624
	ds_read_b128 v[202:205], v99 offset:27648
	ds_read_b128 v[206:209], v99 offset:28672
	ds_read_b128 v[210:213], v99 offset:29696
	ds_read_b128 v[214:217], v99 offset:30720
	ds_read_b128 v[218:221], v99 offset:31744
	s_waitcnt lgkmcnt(7)
	v_pk_add_f32 v[96:97], v[96:97], v[192:193]
	v_pk_add_f32 v[94:95], v[94:95], v[190:191]
	s_waitcnt lgkmcnt(6)
	v_pk_add_f32 v[92:93], v[92:93], v[196:197]
	v_pk_add_f32 v[90:91], v[90:91], v[194:195]
	s_waitcnt lgkmcnt(5)
	v_pk_add_f32 v[88:89], v[88:89], v[200:201]
	v_pk_add_f32 v[86:87], v[86:87], v[198:199]
	s_waitcnt lgkmcnt(4)
	v_pk_add_f32 v[84:85], v[84:85], v[204:205]
	v_pk_add_f32 v[82:83], v[82:83], v[202:203]
	s_waitcnt lgkmcnt(3)
	v_pk_add_f32 v[80:81], v[80:81], v[208:209]
	v_pk_add_f32 v[78:79], v[78:79], v[206:207]
	s_waitcnt lgkmcnt(2)
	v_pk_add_f32 v[76:77], v[76:77], v[212:213]
	v_pk_add_f32 v[74:75], v[74:75], v[210:211]
	s_waitcnt lgkmcnt(1)
	v_pk_add_f32 v[72:73], v[72:73], v[216:217]
	v_pk_add_f32 v[70:71], v[70:71], v[214:215]
	s_waitcnt lgkmcnt(0)
	v_pk_add_f32 v[102:103], v[102:103], v[220:221]
	v_pk_add_f32 v[100:101], v[100:101], v[218:219]
	ds_read_b128 v[190:193], v99 offset:32768
	ds_read_b128 v[194:197], v99 offset:33792
	ds_read_b128 v[198:201], v99 offset:34816
	ds_read_b128 v[202:205], v99 offset:35840
	ds_read_b128 v[206:209], v99 offset:36864
	ds_read_b128 v[210:213], v99 offset:37888
	ds_read_b128 v[214:217], v99 offset:38912
	ds_read_b128 v[218:221], v99 offset:39936
	s_waitcnt lgkmcnt(7)
	v_pk_add_f32 v[94:95], v[94:95], v[190:191]
	v_pk_add_f32 v[96:97], v[96:97], v[192:193]
	s_waitcnt lgkmcnt(6)
	v_pk_add_f32 v[90:91], v[90:91], v[194:195]
	v_pk_add_f32 v[92:93], v[92:93], v[196:197]
	s_waitcnt lgkmcnt(5)
	v_pk_add_f32 v[86:87], v[86:87], v[198:199]
	v_pk_add_f32 v[88:89], v[88:89], v[200:201]
	s_waitcnt lgkmcnt(4)
	v_pk_add_f32 v[82:83], v[82:83], v[202:203]
	v_pk_add_f32 v[84:85], v[84:85], v[204:205]
	s_waitcnt lgkmcnt(3)
	v_pk_add_f32 v[78:79], v[78:79], v[206:207]
	v_pk_add_f32 v[80:81], v[80:81], v[208:209]
	s_waitcnt lgkmcnt(2)
	v_pk_add_f32 v[74:75], v[74:75], v[210:211]
	v_pk_add_f32 v[76:77], v[76:77], v[212:213]
	s_waitcnt lgkmcnt(1)
	v_pk_add_f32 v[70:71], v[70:71], v[214:215]
	v_pk_add_f32 v[72:73], v[72:73], v[216:217]
	s_waitcnt lgkmcnt(0)
	v_pk_add_f32 v[100:101], v[100:101], v[218:219]
	v_pk_add_f32 v[102:103], v[102:103], v[220:221]
	ds_read_b128 v[190:193], v99 offset:40960
	ds_read_b128 v[194:197], v99 offset:41984
	ds_read_b128 v[198:201], v99 offset:43008
	ds_read_b128 v[202:205], v99 offset:44032
	ds_read_b128 v[206:209], v99 offset:45056
	ds_read_b128 v[210:213], v99 offset:46080
	ds_read_b128 v[214:217], v99 offset:47104
	ds_read_b128 v[218:221], v99 offset:48128
	s_waitcnt lgkmcnt(7)
	v_pk_add_f32 v[96:97], v[96:97], v[192:193]
	v_pk_add_f32 v[94:95], v[94:95], v[190:191]
	s_waitcnt lgkmcnt(6)
	v_pk_add_f32 v[92:93], v[92:93], v[196:197]
	v_pk_add_f32 v[90:91], v[90:91], v[194:195]
	s_waitcnt lgkmcnt(5)
	v_pk_add_f32 v[88:89], v[88:89], v[200:201]
	v_pk_add_f32 v[86:87], v[86:87], v[198:199]
	s_waitcnt lgkmcnt(4)
	v_pk_add_f32 v[84:85], v[84:85], v[204:205]
	v_pk_add_f32 v[82:83], v[82:83], v[202:203]
	s_waitcnt lgkmcnt(3)
	v_pk_add_f32 v[80:81], v[80:81], v[208:209]
	v_pk_add_f32 v[78:79], v[78:79], v[206:207]
	s_waitcnt lgkmcnt(2)
	v_pk_add_f32 v[76:77], v[76:77], v[212:213]
	v_pk_add_f32 v[74:75], v[74:75], v[210:211]
	s_waitcnt lgkmcnt(1)
	v_pk_add_f32 v[72:73], v[72:73], v[216:217]
	v_pk_add_f32 v[70:71], v[70:71], v[214:215]
	s_waitcnt lgkmcnt(0)
	v_pk_add_f32 v[102:103], v[102:103], v[220:221]
	v_pk_add_f32 v[100:101], v[100:101], v[218:219]
	ds_read_b128 v[190:193], v99 offset:49152
	ds_read_b128 v[194:197], v99 offset:50176
	ds_read_b128 v[198:201], v99 offset:51200
	ds_read_b128 v[202:205], v99 offset:52224
	ds_read_b128 v[206:209], v99 offset:53248
	s_waitcnt lgkmcnt(4)
	v_pk_add_f32 v[94:95], v[94:95], v[190:191]
	v_pk_add_f32 v[96:97], v[96:97], v[192:193]
	s_waitcnt lgkmcnt(3)
	v_pk_add_f32 v[90:91], v[90:91], v[194:195]
	v_pk_add_f32 v[92:93], v[92:93], v[196:197]
	s_waitcnt lgkmcnt(2)
	v_pk_add_f32 v[86:87], v[86:87], v[198:199]
	v_pk_add_f32 v[88:89], v[88:89], v[200:201]
	s_waitcnt lgkmcnt(1)
	v_pk_add_f32 v[104:105], v[82:83], v[202:203]
	v_pk_add_f32 v[84:85], v[84:85], v[204:205]
	s_waitcnt lgkmcnt(0)
	v_pk_add_f32 v[106:107], v[78:79], v[206:207]
	v_pk_add_f32 v[108:109], v[80:81], v[208:209]
	ds_read_b128 v[66:69], v99 offset:54272
	ds_read_b128 v[80:83], v99 offset:60416
	s_waitcnt lgkmcnt(1)
	v_pk_add_f32 v[110:111], v[74:75], v[66:67]
	v_pk_add_f32 v[112:113], v[76:77], v[68:69]
	ds_read_b128 v[66:69], v99 offset:55296
	ds_read_b128 v[76:79], v99 offset:59392
	s_waitcnt lgkmcnt(2)
	v_pk_add_f32 v[80:81], v[104:105], v[80:81]
	s_waitcnt lgkmcnt(1)
; #define LAS __attribute__((address_space(3)))
; __device__ __forceinline__ void ln_phase(const bf16_t* Z, const bf16_t* RES, const float* part, int nsl, const float* g, const float* b, bf16_t* XB, float* outp, float* outs, int gw, int NGW, int lane,
;                                          LAS float* scr, int wave, int bid, int nblk) {
;     ...
;             for (int w8 = 0; w8 < 8; ++w8)
; #pragma unroll
;                 for (int j = 0; j < 8; ++j) v[j] += *(LAS const f32x4*)(scr + w8 * 2048 + (lane + 64 * j) * 4);
	v_pk_add_f32 v[114:115], v[70:71], v[66:67]
	v_pk_add_f32 v[116:117], v[72:73], v[68:69]
	ds_read_b128 v[66:69], v99 offset:56320
	ds_read_b128 v[72:75], v99 offset:58368
	s_waitcnt lgkmcnt(2)
	v_pk_add_f32 v[76:77], v[86:87], v[76:77]
	s_waitcnt lgkmcnt(1)
	v_pk_add_f32 v[120:121], v[102:103], v[68:69]
	ds_read_b128 v[68:71], v99 offset:57344
	v_pk_add_f32 v[118:119], v[100:101], v[66:67]
	s_waitcnt lgkmcnt(1)
	v_pk_add_f32 v[72:73], v[90:91], v[72:73]
	ds_read_b128 v[100:103], v99 offset:64512
	s_waitcnt lgkmcnt(1)
	v_pk_add_f32 v[66:67], v[96:97], v[70:71]
	v_pk_add_f32 v[68:69], v[94:95], v[68:69]
	v_pk_add_f32 v[70:71], v[92:93], v[74:75]
	v_pk_add_f32 v[74:75], v[88:89], v[78:79]
	v_pk_add_f32 v[78:79], v[84:85], v[82:83]
	ds_read_b128 v[84:87], v99 offset:61440
	ds_read_b128 v[88:91], v99 offset:62464
	ds_read_b128 v[92:95], v99 offset:63488
	s_waitcnt lgkmcnt(3)
	v_pk_add_f32 v[96:97], v[118:119], v[100:101]
	v_mov_b32_e32 v100, v68
	s_waitcnt lgkmcnt(2)
	v_pk_add_f32 v[82:83], v[108:109], v[86:87]
	s_waitcnt lgkmcnt(1)
	v_pk_add_f32 v[86:87], v[112:113], v[90:91]
	s_waitcnt lgkmcnt(0)
	v_pk_add_f32 v[90:91], v[116:117], v[94:95]
	v_pk_add_f32 v[94:95], v[120:121], v[102:103]
	v_mov_b32_e32 v101, v72
	v_mov_b32_e32 v102, v69
	v_mov_b32_e32 v103, v73
	v_pk_add_f32 v[100:101], v[100:101], v[102:103]
	v_mov_b32_e32 v102, v66
	v_mov_b32_e32 v103, v70
	v_mov_b32_e32 v104, v67
	v_mov_b32_e32 v105, v71
	v_pk_add_f32 v[102:103], v[102:103], v[104:105]
	v_mov_b32_e32 v104, v76
	v_pk_add_f32 v[100:101], v[100:101], v[102:103]
	v_pk_mov_b32 v[102:103], v[76:77], v[74:75] op_sel:[1,0]
	v_mov_b32_e32 v105, v75
	v_pk_add_f32 v[102:103], v[102:103], v[104:105]
	v_pk_add_f32 v[84:85], v[106:107], v[84:85]
	v_add_f32_e32 v100, 0, v100
	v_pk_add_f32 v[102:103], v[102:103], v[102:103] op_sel:[0,1] op_sel_hi:[1,0]
	v_add_f32_e32 v100, v100, v101
	v_add_f32_e32 v104, v80, v81
	v_add_f32_e32 v106, v78, v79
	v_mov_b32_e32 v101, v84
	v_mov_b32_e32 v103, v85
	v_mov_b32_e32 v105, v82
	v_mov_b32_e32 v107, v83
	v_pk_add_f32 v[88:89], v[110:111], v[88:89]
	v_pk_add_f32 v[100:101], v[100:101], v[102:103]
	v_pk_add_f32 v[102:103], v[104:105], v[106:107]
	v_mov_b32_e32 v104, v88
	v_pk_add_f32 v[100:101], v[100:101], v[102:103]
	v_pk_mov_b32 v[102:103], v[88:89], v[86:87] op_sel:[1,0]
	v_mov_b32_e32 v105, v87
	v_pk_add_f32 v[102:103], v[102:103], v[104:105]
	v_pk_add_f32 v[92:93], v[114:115], v[92:93]
	v_pk_add_f32 v[100:101], v[100:101], v[100:101] op_sel:[0,1] op_sel_hi:[1,0]
	v_pk_add_f32 v[102:103], v[102:103], v[102:103] op_sel:[0,1] op_sel_hi:[1,0]
	v_add_f32_e32 v104, v92, v93
	v_add_f32_e32 v106, v90, v91
	v_mov_b32_e32 v101, v96
	v_mov_b32_e32 v103, v97
	v_mov_b32_e32 v105, v94
	v_mov_b32_e32 v107, v95
	v_pk_add_f32 v[100:101], v[100:101], v[102:103]
	v_pk_add_f32 v[102:103], v[104:105], v[106:107]
	s_nop 0
	v_pk_add_f32 v[100:101], v[100:101], v[102:103]
	v_xor_b32_e32 v102, 1, v185
	v_add_f32_e32 v100, v100, v101
	v_and_b32_e32 v101, 64, v185
	v_add_u32_e32 v101, 64, v101
	v_cmp_lt_i32_e32 vcc, v102, v101
	s_nop 1
	v_cndmask_b32_e32 v102, v185, v102, vcc
	v_lshlrev_b32_e32 v102, 2, v102
	ds_bpermute_b32 v103, v102, v100
	s_waitcnt lgkmcnt(0)
	v_add_f32_e32 v100, v100, v103
	v_xor_b32_e32 v103, 2, v185
	v_cmp_lt_i32_e32 vcc, v103, v101
	s_nop 1
	v_cndmask_b32_e32 v103, v185, v103, vcc
	v_lshlrev_b32_e32 v103, 2, v103
	ds_bpermute_b32 v104, v103, v100
	s_waitcnt lgkmcnt(0)
	v_add_f32_e32 v100, v100, v104
	v_xor_b32_e32 v104, 4, v185
	v_cmp_lt_i32_e32 vcc, v104, v101
	s_nop 1
	v_cndmask_b32_e32 v104, v185, v104, vcc
	v_lshlrev_b32_e32 v104, 2, v104
	ds_bpermute_b32 v105, v104, v100
	s_waitcnt lgkmcnt(0)
	v_add_f32_e32 v100, v100, v105
	v_xor_b32_e32 v105, 8, v185
	v_cmp_lt_i32_e32 vcc, v105, v101
	s_nop 1
	v_cndmask_b32_e32 v105, v185, v105, vcc
	v_lshlrev_b32_e32 v105, 2, v105
	ds_bpermute_b32 v106, v105, v100
	s_waitcnt lgkmcnt(0)
	v_add_f32_e32 v100, v100, v106
	v_xor_b32_e32 v106, 16, v185
	v_cmp_lt_i32_e32 vcc, v106, v101
	s_nop 1
	v_cndmask_b32_e32 v106, v185, v106, vcc
	v_lshlrev_b32_e32 v106, 2, v106
	ds_bpermute_b32 v107, v106, v100
	s_waitcnt lgkmcnt(0)
	v_add_f32_e32 v100, v100, v107
	v_xor_b32_e32 v107, 32, v185
	v_cmp_lt_i32_e32 vcc, v107, v101
	s_nop 1
	v_cndmask_b32_e32 v101, v185, v107, vcc
	v_lshlrev_b32_e32 v101, 2, v101
	ds_bpermute_b32 v107, v101, v100
	s_andn2_b64 vcc, exec, s[40:41]
	s_waitcnt lgkmcnt(0)
	v_add_f32_e32 v100, v100, v107
	v_fmamk_f32 v67, v100, 0xba000000, v67
	v_fmamk_f32 v69, v100, 0xba000000, v69
	v_fmac_f32_e32 v66, 0xba000000, v100
	v_fmac_f32_e32 v68, 0xba000000, v100
	v_mul_f32_e32 v107, v69, v69
	v_mul_f32_e32 v108, v67, v67
	v_fmac_f32_e32 v107, v68, v68
	v_fmac_f32_e32 v108, v66, v66
	v_fmamk_f32 v71, v100, 0xba000000, v71
	v_fmamk_f32 v73, v100, 0xba000000, v73
	v_add_f32_e32 v107, v107, v108
	v_fmac_f32_e32 v70, 0xba000000, v100
	v_fmac_f32_e32 v72, 0xba000000, v100
	v_mul_f32_e32 v108, v73, v73
	v_mul_f32_e32 v109, v71, v71
	v_fmac_f32_e32 v108, v72, v72
	v_fmac_f32_e32 v109, v70, v70
	v_add_f32_e32 v108, v108, v109
	v_fmamk_f32 v75, v100, 0xba000000, v75
	v_fmamk_f32 v77, v100, 0xba000000, v77
	v_add_f32_e32 v107, v107, v108
	v_fmac_f32_e32 v74, 0xba000000, v100
	v_fmac_f32_e32 v76, 0xba000000, v100
	v_mul_f32_e32 v108, v77, v77
	v_mul_f32_e32 v109, v75, v75
	v_fmac_f32_e32 v108, v76, v76
	v_fmac_f32_e32 v109, v74, v74
	v_add_f32_e32 v108, v108, v109
	v_fmamk_f32 v79, v100, 0xba000000, v79
	v_fmamk_f32 v81, v100, 0xba000000, v81
	v_add_f32_e32 v107, v108, v107
	v_fmac_f32_e32 v78, 0xba000000, v100
	v_fmac_f32_e32 v80, 0xba000000, v100
	v_mul_f32_e32 v108, v81, v81
	v_mul_f32_e32 v109, v79, v79
	v_fmac_f32_e32 v108, v80, v80
	v_fmac_f32_e32 v109, v78, v78
	v_add_f32_e32 v108, v108, v109
	v_fmamk_f32 v83, v100, 0xba000000, v83
	v_fmamk_f32 v85, v100, 0xba000000, v85
	v_add_f32_e32 v107, v108, v107
	v_fmac_f32_e32 v82, 0xba000000, v100
	v_fmac_f32_e32 v84, 0xba000000, v100
	v_mul_f32_e32 v108, v85, v85
	v_mul_f32_e32 v109, v83, v83
	v_fmac_f32_e32 v108, v84, v84
	v_fmac_f32_e32 v109, v82, v82
	v_add_f32_e32 v108, v108, v109
	v_fmamk_f32 v87, v100, 0xba000000, v87
	v_fmamk_f32 v89, v100, 0xba000000, v89
	v_add_f32_e32 v107, v108, v107
	v_fmac_f32_e32 v86, 0xba000000, v100
	v_fmac_f32_e32 v88, 0xba000000, v100
	v_mul_f32_e32 v108, v89, v89
	v_mul_f32_e32 v109, v87, v87
	v_fmac_f32_e32 v108, v88, v88
	v_fmac_f32_e32 v109, v86, v86
	v_add_f32_e32 v108, v108, v109
	v_fmamk_f32 v91, v100, 0xba000000, v91
	v_fmamk_f32 v93, v100, 0xba000000, v93
	v_add_f32_e32 v107, v108, v107
	v_fmac_f32_e32 v90, 0xba000000, v100
	v_fmac_f32_e32 v92, 0xba000000, v100
	v_mul_f32_e32 v108, v93, v93
	v_mul_f32_e32 v109, v91, v91
	v_fmac_f32_e32 v108, v92, v92
	v_fmac_f32_e32 v109, v90, v90
	v_add_f32_e32 v108, v108, v109
	v_fmamk_f32 v95, v100, 0xba000000, v95
	v_fmamk_f32 v97, v100, 0xba000000, v97
	v_add_f32_e32 v107, v108, v107
	v_fmac_f32_e32 v94, 0xba000000, v100
	v_fmac_f32_e32 v96, 0xba000000, v100
	v_mul_f32_e32 v100, v97, v97
	v_mul_f32_e32 v108, v95, v95
	v_fmac_f32_e32 v100, v96, v96
	v_fmac_f32_e32 v108, v94, v94
	v_add_f32_e32 v100, v100, v108
	v_add_f32_e32 v100, v100, v107
	ds_bpermute_b32 v102, v102, v100
	s_waitcnt lgkmcnt(0)
	v_add_f32_e32 v100, v100, v102
	ds_bpermute_b32 v102, v103, v100
	s_waitcnt lgkmcnt(0)
	v_add_f32_e32 v100, v100, v102
	ds_bpermute_b32 v102, v104, v100
	s_waitcnt lgkmcnt(0)
	v_add_f32_e32 v100, v100, v102
	ds_bpermute_b32 v102, v105, v100
	s_waitcnt lgkmcnt(0)
	v_add_f32_e32 v100, v100, v102
	ds_bpermute_b32 v102, v106, v100
	s_waitcnt lgkmcnt(0)
	v_add_f32_e32 v100, v100, v102
	ds_bpermute_b32 v101, v101, v100
	s_cbranch_vccnz .LBB0_911
	s_waitcnt lgkmcnt(0)
	v_add_f32_e32 v100, v100, v101
	v_fmamk_f32 v100, v100, 0x3a000000, v181
	v_mul_f32_e32 v101, 0x4f800000, v100
	v_cmp_gt_f32_e32 vcc, s65, v100
	v_readlane_b32 s8, v254, 59
	v_readlane_b32 s9, v254, 60
	v_cndmask_b32_e32 v100, v100, v101, vcc
	v_sqrt_f32_e32 v101, v100
	s_nop 0
	v_add_u32_e32 v102, -1, v101
	v_fma_f32 v104, -v102, v101, v100
	v_add_u32_e32 v103, 1, v101
	v_cmp_ge_f32_e64 s[0:1], 0, v104
	s_nop 1
	v_cndmask_b32_e64 v102, v101, v102, s[0:1]
	v_fma_f32 v101, -v103, v101, v100
	v_cmp_lt_f32_e64 s[0:1], 0, v101
	s_nop 1
	v_cndmask_b32_e64 v101, v102, v103, s[0:1]
	v_mul_f32_e32 v102, 0x37800000, v101
	v_cndmask_b32_e32 v101, v101, v102, vcc
	v_cmp_class_f32_e32 vcc, v100, v182
	s_nop 1
	v_cndmask_b32_e32 v100, v101, v100, vcc
	v_div_scale_f32 v101, s[0:1], v100, v100, 1.0
	v_rcp_f32_e32 v102, v101
	s_lshl_b64 s[0:1], s[44:45], 11
	s_lshl_b64 s[0:1], s[0:1], 2
	s_add_u32 s8, s8, s0
	v_fma_f32 v103, -v101, v102, 1.0
	v_fmac_f32_e32 v102, v103, v102
	v_div_scale_f32 v103, vcc, 1.0, v100, 1.0
	v_mul_f32_e32 v104, v103, v102
	v_fma_f32 v105, -v101, v104, v103
	v_fmac_f32_e32 v104, v105, v102
	v_fma_f32 v101, -v101, v104, v103
	v_div_fmas_f32 v101, v101, v102, v104
	v_div_fixup_f32 v100, v101, v100, 1.0
	v_pk_mul_f32 v[102:103], v[96:97], v[100:101] op_sel_hi:[1,0]
	v_pk_mul_f32 v[94:95], v[94:95], v[100:101] op_sel_hi:[1,0]
	v_pk_mul_f32 v[90:91], v[90:91], v[100:101] op_sel_hi:[1,0]
	v_pk_fma_f32 v[96:97], v[60:61], v[94:95], v[64:65]
	v_pk_fma_f32 v[94:95], v[58:59], v[102:103], v[62:63]
	v_pk_mul_f32 v[102:103], v[92:93], v[100:101] op_sel_hi:[1,0]
	v_pk_fma_f32 v[92:93], v[52:53], v[90:91], v[56:57]
	v_pk_fma_f32 v[90:91], v[50:51], v[102:103], v[54:55]
	v_pk_mul_f32 v[102:103], v[88:89], v[100:101] op_sel_hi:[1,0]
	v_pk_mul_f32 v[86:87], v[86:87], v[100:101] op_sel_hi:[1,0]
	v_pk_mul_f32 v[82:83], v[82:83], v[100:101] op_sel_hi:[1,0]
	v_pk_fma_f32 v[88:89], v[44:45], v[86:87], v[48:49]
	v_pk_fma_f32 v[86:87], v[42:43], v[102:103], v[46:47]
	v_pk_mul_f32 v[102:103], v[84:85], v[100:101] op_sel_hi:[1,0]
	s_addc_u32 s9, s9, s1
	s_lshl_b64 s[0:1], s[2:3], 13
	v_pk_fma_f32 v[84:85], v[36:37], v[82:83], v[40:41]
	v_pk_fma_f32 v[82:83], v[34:35], v[102:103], v[38:39]
	v_pk_mul_f32 v[102:103], v[80:81], v[100:101] op_sel_hi:[1,0]
	v_pk_mul_f32 v[78:79], v[78:79], v[100:101] op_sel_hi:[1,0]
	s_add_u32 s0, s6, s0
	v_pk_fma_f32 v[80:81], v[28:29], v[78:79], v[32:33]
	v_pk_fma_f32 v[78:79], v[26:27], v[102:103], v[30:31]
	v_pk_mul_f32 v[102:103], v[76:77], v[100:101] op_sel_hi:[1,0]
	v_pk_mul_f32 v[74:75], v[74:75], v[100:101] op_sel_hi:[1,0]
	s_addc_u32 s1, s7, s1
	v_pk_fma_f32 v[76:77], v[20:21], v[74:75], v[24:25]
	v_pk_fma_f32 v[74:75], v[18:19], v[102:103], v[22:23]
	v_pk_mul_f32 v[102:103], v[72:73], v[100:101] op_sel_hi:[1,0]
	v_pk_mul_f32 v[70:71], v[70:71], v[100:101] op_sel_hi:[1,0]
	s_cmp_lt_i32 s2, 0
	v_pk_fma_f32 v[72:73], v[12:13], v[70:71], v[16:17]
	v_pk_fma_f32 v[70:71], v[10:11], v[102:103], v[14:15]
	v_pk_mul_f32 v[102:103], v[68:69], v[100:101] op_sel_hi:[1,0]
	v_pk_mul_f32 v[66:67], v[66:67], v[100:101] op_sel_hi:[1,0]
	s_cselect_b32 s1, s9, s1
	s_cselect_b32 s0, s8, s0
	v_pk_fma_f32 v[68:69], v[4:5], v[66:67], v[8:9]
	v_pk_fma_f32 v[66:67], v[2:3], v[102:103], v[6:7]
	v_lshl_add_u64 v[100:101], s[0:1], 0, v[0:1]
	global_store_dwordx4 v0, v[66:69], s[0:1]
	global_store_dwordx4 v0, v[70:73], s[0:1] offset:1024
	global_store_dwordx4 v0, v[74:77], s[0:1] offset:2048
	global_store_dwordx4 v0, v[78:81], s[0:1] offset:3072
	v_add_co_u32_e32 v66, vcc, 0x1000, v100
	s_nop 1
	v_addc_co_u32_e32 v67, vcc, 0, v101, vcc
	global_store_dwordx4 v[66:67], v[82:85], off
	global_store_dwordx4 v[66:67], v[86:89], off offset:1024
	global_store_dwordx4 v[66:67], v[90:93], off offset:2048
	global_store_dwordx4 v[66:67], v[94:97], off offset:3072
	s_branch .LBB0_911

; #define LAS __attribute__((address_space(3)))
; #define GAS __attribute__((address_space(1)))
; __device__ __forceinline__ float bflo(unsigned u) { return __uint_as_float(u << 16); }
; __device__ __forceinline__ float bfhi(unsigned u) { return __uint_as_float(u & 0xffff0000u); }
; __device__ __forceinline__ void ln_phase(const bf16_t* Z, const bf16_t* RES, const float* part, int nsl, const float* g, const float* b, bf16_t* XB, float* outp, float* outs, int gw, int NGW, int lane,
;                                          LAS float* scr, int wave, int bid, int nblk) {
;     ...
;         for (int j = 0; j < 8; ++j) *(LAS f32x4*)(scr + wave * 2048 + (lane + 64 * j) * 4) = acc[j];
;         __syncthreads();
;         if (wave == 0) { const GAS u32x2* z_ = (const GAS u32x2*)(RES + (size_t)(MP + r) * DM) + lane; f32x4 v[8];
; #pragma unroll
;             for (int j = 0; j < 8; ++j) { const u32x2 w = z_[64 * j]; v[j] = (f32x4){ALPHA * bflo(w.x), ALPHA * bfhi(w.x), ALPHA * bflo(w.y), ALPHA * bfhi(w.y)}; }
; #pragma unroll
;             for (int w8 = 0; w8 < 8; ++w8)
; #pragma unroll
;                 for (int j = 0; j < 8; ++j) v[j] += *(LAS const f32x4*)(scr + w8 * 2048 + (lane + 64 * j) * 4);
.LBB0_933:
	v_add_u32_e32 v98, s67, v0
	s_and_b64 vcc, exec, s[80:81]
	ds_write_b128 v98, v[90:93]
	ds_write_b128 v98, v[94:97] offset:1024
	ds_write_b128 v98, v[86:89] offset:2048
	ds_write_b128 v98, v[82:85] offset:3072
	ds_write_b128 v98, v[78:81] offset:4096
	ds_write_b128 v98, v[74:77] offset:5120
	ds_write_b128 v98, v[70:73] offset:6144
	ds_write_b128 v98, v[66:69] offset:7168
	s_waitcnt lgkmcnt(0)
	s_barrier
	s_cbranch_vccz .LBB0_929
	s_ashr_i32 s41, s40, 31
	s_lshl_b64 s[0:1], s[40:41], 12
	s_add_u32 s0, s30, s0
	s_addc_u32 s1, s31, s1
	v_lshlrev_b32_e32 v66, 3, v102
	v_mov_b32_e32 v67, v1
	v_lshl_add_u64 v[68:69], s[0:1], 0, v[66:67]
	s_mov_b64 s[0:1], 0x4000000
	v_lshl_add_u64 v[66:67], v[68:69], 0, s[0:1]
	v_add_co_u32_e32 v68, vcc, 0x4000000, v68
	s_nop 1
	v_addc_co_u32_e32 v69, vcc, 0, v69, vcc
	global_load_dwordx2 v[222:223], v[68:69], off
	global_load_dwordx2 v[224:225], v[66:67], off offset:512
	global_load_dwordx2 v[226:227], v[66:67], off offset:1024
	global_load_dwordx2 v[228:229], v[66:67], off offset:1536
	global_load_dwordx2 v[142:143], v[66:67], off offset:2048
	global_load_dwordx2 v[144:145], v[66:67], off offset:2560
	global_load_dwordx2 v[146:147], v[66:67], off offset:3072
	global_load_dwordx2 v[148:149], v[66:67], off offset:3584
	s_waitcnt vmcnt(0)
	v_lshlrev_b32_e32 v74, 16, v222
	v_and_b32_e32 v75, 0xffff0000, v222
	v_lshlrev_b32_e32 v76, 16, v223
	v_and_b32_e32 v77, 0xffff0000, v223
	v_lshlrev_b32_e32 v78, 16, v224
	v_and_b32_e32 v79, 0xffff0000, v224
	v_lshlrev_b32_e32 v80, 16, v225
	v_and_b32_e32 v81, 0xffff0000, v225
	v_lshlrev_b32_e32 v82, 16, v226
	v_and_b32_e32 v83, 0xffff0000, v226
	v_lshlrev_b32_e32 v84, 16, v227
	v_and_b32_e32 v85, 0xffff0000, v227
	v_lshlrev_b32_e32 v86, 16, v228
	v_and_b32_e32 v87, 0xffff0000, v228
	v_lshlrev_b32_e32 v88, 16, v229
	v_and_b32_e32 v89, 0xffff0000, v229
	v_lshlrev_b32_e32 v90, 16, v142
	v_and_b32_e32 v91, 0xffff0000, v142
	v_lshlrev_b32_e32 v92, 16, v143
	v_and_b32_e32 v93, 0xffff0000, v143
	v_lshlrev_b32_e32 v94, 16, v144
	v_and_b32_e32 v95, 0xffff0000, v144
	v_lshlrev_b32_e32 v96, 16, v145
	v_and_b32_e32 v97, 0xffff0000, v145
	v_lshlrev_b32_e32 v98, 16, v146
	v_and_b32_e32 v99, 0xffff0000, v146
	v_lshlrev_b32_e32 v100, 16, v147
	v_and_b32_e32 v101, 0xffff0000, v147
	v_lshlrev_b32_e32 v104, 16, v148
	v_and_b32_e32 v105, 0xffff0000, v148
	v_lshlrev_b32_e32 v106, 16, v149
	v_and_b32_e32 v107, 0xffff0000, v149
	ds_read_b128 v[190:193], v103
	ds_read_b128 v[194:197], v103 offset:1024
	ds_read_b128 v[198:201], v103 offset:2048
	ds_read_b128 v[202:205], v103 offset:3072
	ds_read_b128 v[206:209], v103 offset:4096
	ds_read_b128 v[210:213], v103 offset:5120
	ds_read_b128 v[214:217], v103 offset:6144
	ds_read_b128 v[218:221], v103 offset:7168
	s_waitcnt lgkmcnt(7)
	v_pk_fma_f32 v[74:75], v[74:75], s[52:53], v[190:191] op_sel_hi:[1, 0, 1]
	v_pk_fma_f32 v[76:77], v[76:77], s[52:53], v[192:193] op_sel_hi:[1, 0, 1]
	s_waitcnt lgkmcnt(6)
	v_pk_fma_f32 v[78:79], v[78:79], s[52:53], v[194:195] op_sel_hi:[1, 0, 1]
	v_pk_fma_f32 v[80:81], v[80:81], s[52:53], v[196:197] op_sel_hi:[1, 0, 1]
	s_waitcnt lgkmcnt(5)
	v_pk_fma_f32 v[108:109], v[82:83], s[52:53], v[198:199] op_sel_hi:[1, 0, 1]
	v_pk_fma_f32 v[82:83], v[84:85], s[52:53], v[200:201] op_sel_hi:[1, 0, 1]
	s_waitcnt lgkmcnt(4)
	v_pk_fma_f32 v[110:111], v[86:87], s[52:53], v[202:203] op_sel_hi:[1, 0, 1]
	v_pk_fma_f32 v[112:113], v[88:89], s[52:53], v[204:205] op_sel_hi:[1, 0, 1]
	s_waitcnt lgkmcnt(3)
	v_pk_fma_f32 v[114:115], v[90:91], s[52:53], v[206:207] op_sel_hi:[1, 0, 1]
	v_pk_fma_f32 v[116:117], v[92:93], s[52:53], v[208:209] op_sel_hi:[1, 0, 1]
	s_waitcnt lgkmcnt(2)
	v_pk_fma_f32 v[118:119], v[94:95], s[52:53], v[210:211] op_sel_hi:[1, 0, 1]
	v_pk_fma_f32 v[120:121], v[96:97], s[52:53], v[212:213] op_sel_hi:[1, 0, 1]
	s_waitcnt lgkmcnt(1)
	v_pk_fma_f32 v[98:99], v[98:99], s[52:53], v[214:215] op_sel_hi:[1, 0, 1]
	v_pk_fma_f32 v[100:101], v[100:101], s[52:53], v[216:217] op_sel_hi:[1, 0, 1]
	s_waitcnt lgkmcnt(0)
	v_pk_fma_f32 v[94:95], v[104:105], s[52:53], v[218:219] op_sel_hi:[1, 0, 1]
	v_pk_fma_f32 v[96:97], v[106:107], s[52:53], v[220:221] op_sel_hi:[1, 0, 1]
	ds_read_b128 v[190:193], v103 offset:8192
	ds_read_b128 v[194:197], v103 offset:13312
	ds_read_b128 v[198:201], v103 offset:9216
	ds_read_b128 v[202:205], v103 offset:10240
	ds_read_b128 v[206:209], v103 offset:11264
	ds_read_b128 v[210:213], v103 offset:12288
	ds_read_b128 v[214:217], v103 offset:14336
	ds_read_b128 v[218:221], v103 offset:15360
	s_waitcnt lgkmcnt(7)
	v_pk_add_f32 v[90:91], v[76:77], v[192:193]
	v_pk_add_f32 v[92:93], v[74:75], v[190:191]
	s_waitcnt lgkmcnt(5)
	v_pk_add_f32 v[86:87], v[80:81], v[200:201]
	v_pk_add_f32 v[88:89], v[78:79], v[198:199]
	s_waitcnt lgkmcnt(4)
	v_pk_add_f32 v[82:83], v[82:83], v[204:205]
	v_pk_add_f32 v[84:85], v[108:109], v[202:203]
	s_waitcnt lgkmcnt(3)
	v_pk_add_f32 v[78:79], v[112:113], v[208:209]
	v_pk_add_f32 v[80:81], v[110:111], v[206:207]
	s_waitcnt lgkmcnt(2)
	v_pk_add_f32 v[74:75], v[116:117], v[212:213]
	v_pk_add_f32 v[76:77], v[114:115], v[210:211]
	v_pk_add_f32 v[70:71], v[120:121], v[196:197]
	v_pk_add_f32 v[72:73], v[118:119], v[194:195]
	s_waitcnt lgkmcnt(1)
	v_pk_add_f32 v[106:107], v[100:101], v[216:217]
	v_pk_add_f32 v[104:105], v[98:99], v[214:215]
	s_waitcnt lgkmcnt(0)
	v_pk_add_f32 v[100:101], v[96:97], v[220:221]
	v_pk_add_f32 v[98:99], v[94:95], v[218:219]
	ds_read_b128 v[190:193], v103 offset:16384
	ds_read_b128 v[194:197], v103 offset:17408
	ds_read_b128 v[198:201], v103 offset:18432
	ds_read_b128 v[202:205], v103 offset:19456
	ds_read_b128 v[206:209], v103 offset:20480
	ds_read_b128 v[210:213], v103 offset:21504
	ds_read_b128 v[214:217], v103 offset:22528
	ds_read_b128 v[218:221], v103 offset:23552
	s_waitcnt lgkmcnt(7)
; #define LAS __attribute__((address_space(3)))
; __device__ __forceinline__ void ln_phase(const bf16_t* Z, const bf16_t* RES, const float* part, int nsl, const float* g, const float* b, bf16_t* XB, float* outp, float* outs, int gw, int NGW, int lane,
;                                          LAS float* scr, int wave, int bid, int nblk) {
;     ...
;             for (int w8 = 0; w8 < 8; ++w8)
; #pragma unroll
;                 for (int j = 0; j < 8; ++j) v[j] += *(LAS const f32x4*)(scr + w8 * 2048 + (lane + 64 * j) * 4);
	v_pk_add_f32 v[94:95], v[92:93], v[190:191]
	v_pk_add_f32 v[96:97], v[90:91], v[192:193]
	s_waitcnt lgkmcnt(6)
	v_pk_add_f32 v[90:91], v[88:89], v[194:195]
	v_pk_add_f32 v[92:93], v[86:87], v[196:197]
	s_waitcnt lgkmcnt(5)
	v_pk_add_f32 v[86:87], v[84:85], v[198:199]
	v_pk_add_f32 v[88:89], v[82:83], v[200:201]
	s_waitcnt lgkmcnt(4)
	v_pk_add_f32 v[82:83], v[80:81], v[202:203]
	v_pk_add_f32 v[84:85], v[78:79], v[204:205]
	s_waitcnt lgkmcnt(3)
	v_pk_add_f32 v[78:79], v[76:77], v[206:207]
	v_pk_add_f32 v[80:81], v[74:75], v[208:209]
	s_waitcnt lgkmcnt(2)
	v_pk_add_f32 v[74:75], v[72:73], v[210:211]
	v_pk_add_f32 v[76:77], v[70:71], v[212:213]
	s_waitcnt lgkmcnt(1)
	v_pk_add_f32 v[104:105], v[104:105], v[214:215]
	v_pk_add_f32 v[106:107], v[106:107], v[216:217]
	s_waitcnt lgkmcnt(0)
	v_pk_add_f32 v[98:99], v[98:99], v[218:219]
	v_pk_add_f32 v[100:101], v[100:101], v[220:221]
	ds_read_b128 v[190:193], v103 offset:24576
	ds_read_b128 v[194:197], v103 offset:25600
	ds_read_b128 v[198:201], v103 offset:26624
	ds_read_b128 v[202:205], v103 offset:27648
	ds_read_b128 v[206:209], v103 offset:28672
	ds_read_b128 v[210:213], v103 offset:29696
	ds_read_b128 v[214:217], v103 offset:30720
	ds_read_b128 v[218:221], v103 offset:31744
	s_waitcnt lgkmcnt(7)
	v_pk_add_f32 v[96:97], v[96:97], v[192:193]
	v_pk_add_f32 v[94:95], v[94:95], v[190:191]
	s_waitcnt lgkmcnt(6)
	v_pk_add_f32 v[92:93], v[92:93], v[196:197]
	v_pk_add_f32 v[90:91], v[90:91], v[194:195]
	s_waitcnt lgkmcnt(5)
	v_pk_add_f32 v[88:89], v[88:89], v[200:201]
	v_pk_add_f32 v[86:87], v[86:87], v[198:199]
	s_waitcnt lgkmcnt(4)
	v_pk_add_f32 v[84:85], v[84:85], v[204:205]
	v_pk_add_f32 v[82:83], v[82:83], v[202:203]
	s_waitcnt lgkmcnt(3)
	v_pk_add_f32 v[80:81], v[80:81], v[208:209]
	v_pk_add_f32 v[78:79], v[78:79], v[206:207]
	s_waitcnt lgkmcnt(2)
	v_pk_add_f32 v[76:77], v[76:77], v[212:213]
	v_pk_add_f32 v[74:75], v[74:75], v[210:211]
	s_waitcnt lgkmcnt(1)
	v_pk_add_f32 v[106:107], v[106:107], v[216:217]
	v_pk_add_f32 v[104:105], v[104:105], v[214:215]
	s_waitcnt lgkmcnt(0)
	v_pk_add_f32 v[100:101], v[100:101], v[220:221]
	v_pk_add_f32 v[98:99], v[98:99], v[218:219]
	ds_read_b128 v[190:193], v103 offset:32768
	ds_read_b128 v[194:197], v103 offset:33792
	ds_read_b128 v[198:201], v103 offset:34816
	ds_read_b128 v[202:205], v103 offset:35840
	ds_read_b128 v[206:209], v103 offset:36864
	ds_read_b128 v[210:213], v103 offset:37888
	ds_read_b128 v[214:217], v103 offset:38912
	ds_read_b128 v[218:221], v103 offset:39936
	s_waitcnt lgkmcnt(7)
	v_pk_add_f32 v[94:95], v[94:95], v[190:191]
	v_pk_add_f32 v[96:97], v[96:97], v[192:193]
	s_waitcnt lgkmcnt(6)
	v_pk_add_f32 v[90:91], v[90:91], v[194:195]
	v_pk_add_f32 v[92:93], v[92:93], v[196:197]
	s_waitcnt lgkmcnt(5)
	v_pk_add_f32 v[86:87], v[86:87], v[198:199]
	v_pk_add_f32 v[88:89], v[88:89], v[200:201]
	s_waitcnt lgkmcnt(4)
	v_pk_add_f32 v[82:83], v[82:83], v[202:203]
	v_pk_add_f32 v[84:85], v[84:85], v[204:205]
	s_waitcnt lgkmcnt(3)
	v_pk_add_f32 v[78:79], v[78:79], v[206:207]
	v_pk_add_f32 v[80:81], v[80:81], v[208:209]
	s_waitcnt lgkmcnt(2)
	v_pk_add_f32 v[74:75], v[74:75], v[210:211]
	v_pk_add_f32 v[76:77], v[76:77], v[212:213]
	s_waitcnt lgkmcnt(1)
	v_pk_add_f32 v[104:105], v[104:105], v[214:215]
	v_pk_add_f32 v[106:107], v[106:107], v[216:217]
	s_waitcnt lgkmcnt(0)
	v_pk_add_f32 v[98:99], v[98:99], v[218:219]
	v_pk_add_f32 v[100:101], v[100:101], v[220:221]
	ds_read_b128 v[190:193], v103 offset:40960
	ds_read_b128 v[194:197], v103 offset:41984
	ds_read_b128 v[198:201], v103 offset:43008
	ds_read_b128 v[202:205], v103 offset:44032
	ds_read_b128 v[206:209], v103 offset:45056
	ds_read_b128 v[210:213], v103 offset:46080
	ds_read_b128 v[214:217], v103 offset:47104
	ds_read_b128 v[218:221], v103 offset:48128
	s_waitcnt lgkmcnt(7)
	v_pk_add_f32 v[96:97], v[96:97], v[192:193]
	v_pk_add_f32 v[94:95], v[94:95], v[190:191]
	s_waitcnt lgkmcnt(6)
	v_pk_add_f32 v[92:93], v[92:93], v[196:197]
	v_pk_add_f32 v[90:91], v[90:91], v[194:195]
	s_waitcnt lgkmcnt(5)
	v_pk_add_f32 v[88:89], v[88:89], v[200:201]
	v_pk_add_f32 v[86:87], v[86:87], v[198:199]
	s_waitcnt lgkmcnt(4)
	v_pk_add_f32 v[84:85], v[84:85], v[204:205]
	v_pk_add_f32 v[82:83], v[82:83], v[202:203]
	s_waitcnt lgkmcnt(3)
	v_pk_add_f32 v[80:81], v[80:81], v[208:209]
	v_pk_add_f32 v[78:79], v[78:79], v[206:207]
	s_waitcnt lgkmcnt(2)
	v_pk_add_f32 v[76:77], v[76:77], v[212:213]
	v_pk_add_f32 v[74:75], v[74:75], v[210:211]
	s_waitcnt lgkmcnt(1)
	v_pk_add_f32 v[106:107], v[106:107], v[216:217]
	v_pk_add_f32 v[104:105], v[104:105], v[214:215]
	s_waitcnt lgkmcnt(0)
	v_pk_add_f32 v[100:101], v[100:101], v[220:221]
	v_pk_add_f32 v[98:99], v[98:99], v[218:219]
	ds_read_b128 v[190:193], v103 offset:49152
	ds_read_b128 v[194:197], v103 offset:50176
	ds_read_b128 v[198:201], v103 offset:51200
	ds_read_b128 v[202:205], v103 offset:52224
	ds_read_b128 v[206:209], v103 offset:53248
	s_waitcnt lgkmcnt(4)
	v_pk_add_f32 v[94:95], v[94:95], v[190:191]
	v_pk_add_f32 v[96:97], v[96:97], v[192:193]
	s_waitcnt lgkmcnt(3)
	v_pk_add_f32 v[90:91], v[90:91], v[194:195]
	v_pk_add_f32 v[92:93], v[92:93], v[196:197]
	s_waitcnt lgkmcnt(2)
	v_pk_add_f32 v[86:87], v[86:87], v[198:199]
	v_pk_add_f32 v[88:89], v[88:89], v[200:201]
	s_waitcnt lgkmcnt(1)
	v_pk_add_f32 v[108:109], v[82:83], v[202:203]
	v_pk_add_f32 v[110:111], v[84:85], v[204:205]
	s_waitcnt lgkmcnt(0)
	v_pk_add_f32 v[112:113], v[78:79], v[206:207]
	v_pk_add_f32 v[114:115], v[80:81], v[208:209]
	ds_read_b128 v[70:73], v103 offset:54272
	ds_read_b128 v[80:83], v103 offset:59392
	s_waitcnt lgkmcnt(1)
; #define LAS __attribute__((address_space(3)))
; __device__ __forceinline__ void ln_phase(const bf16_t* Z, const bf16_t* RES, const float* part, int nsl, const float* g, const float* b, bf16_t* XB, float* outp, float* outs, int gw, int NGW, int lane,
;                                          LAS float* scr, int wave, int bid, int nblk) {
;     ...
;             for (int w8 = 0; w8 < 8; ++w8)
; #pragma unroll
;                 for (int j = 0; j < 8; ++j) v[j] += *(LAS const f32x4*)(scr + w8 * 2048 + (lane + 64 * j) * 4);
	v_pk_add_f32 v[116:117], v[74:75], v[70:71]
	v_pk_add_f32 v[118:119], v[76:77], v[72:73]
	ds_read_b128 v[70:73], v103 offset:55296
	ds_read_b128 v[76:79], v103 offset:58368
	s_waitcnt lgkmcnt(2)
	v_pk_add_f32 v[80:81], v[86:87], v[80:81]
	ds_read_b128 v[84:87], v103 offset:60416
	s_waitcnt lgkmcnt(2)
	v_pk_add_f32 v[104:105], v[104:105], v[70:71]
	v_pk_add_f32 v[106:107], v[106:107], v[72:73]
	ds_read_b128 v[70:73], v103 offset:56320
	s_waitcnt lgkmcnt(2)
	v_pk_add_f32 v[76:77], v[90:91], v[76:77]
	s_waitcnt lgkmcnt(1)
	v_pk_add_f32 v[84:85], v[108:109], v[84:85]
	s_waitcnt lgkmcnt(0)
	v_pk_add_f32 v[100:101], v[100:101], v[72:73]
	ds_read_b128 v[72:75], v103 offset:57344
	v_pk_add_f32 v[120:121], v[98:99], v[70:71]
	s_waitcnt lgkmcnt(0)
	v_pk_add_f32 v[70:71], v[96:97], v[74:75]
	v_pk_add_f32 v[72:73], v[94:95], v[72:73]
	v_pk_add_f32 v[74:75], v[92:93], v[78:79]
	v_pk_add_f32 v[78:79], v[88:89], v[82:83]
	ds_read_b128 v[88:91], v103 offset:61440
	ds_read_b128 v[92:95], v103 offset:62464
	ds_read_b128 v[96:99], v103 offset:63488
	v_pk_add_f32 v[82:83], v[110:111], v[86:87]
	v_mov_b32_e32 v108, v71
	s_waitcnt lgkmcnt(2)
	v_pk_add_f32 v[86:87], v[114:115], v[90:91]
	s_waitcnt lgkmcnt(1)
	v_pk_add_f32 v[90:91], v[118:119], v[94:95]
	s_waitcnt lgkmcnt(0)
	v_pk_add_f32 v[94:95], v[106:107], v[98:99]
	v_pk_add_f32 v[96:97], v[104:105], v[96:97]
	ds_read_b128 v[104:107], v103 offset:64512
	v_mov_b32_e32 v109, v75
	v_pk_add_f32 v[88:89], v[112:113], v[88:89]
	v_add_f32_e32 v110, v82, v83
	v_mov_b32_e32 v111, v87
	s_waitcnt lgkmcnt(0)
	v_pk_add_f32 v[98:99], v[100:101], v[106:107]
	v_pk_add_f32 v[100:101], v[120:121], v[104:105]
	v_mov_b32_e32 v104, v72
	v_mov_b32_e32 v105, v76
	v_mov_b32_e32 v106, v73
	v_mov_b32_e32 v107, v77
	v_pk_add_f32 v[104:105], v[104:105], v[106:107]
	v_mov_b32_e32 v106, v70
	v_mov_b32_e32 v107, v74
	v_pk_add_f32 v[106:107], v[106:107], v[108:109]
	v_mov_b32_e32 v108, v80
	v_pk_add_f32 v[104:105], v[104:105], v[106:107]
	v_pk_mov_b32 v[106:107], v[80:81], v[78:79] op_sel:[1,0]
	v_mov_b32_e32 v109, v79
	v_pk_add_f32 v[106:107], v[106:107], v[108:109]
	v_add_f32_e32 v104, 0, v104
	v_pk_add_f32 v[106:107], v[106:107], v[106:107] op_sel:[0,1] op_sel_hi:[1,0]
	v_add_f32_e32 v104, v104, v105
	v_add_f32_e32 v108, v84, v85
	v_mov_b32_e32 v105, v88
	v_mov_b32_e32 v107, v89
	v_mov_b32_e32 v109, v86
	v_pk_add_f32 v[92:93], v[116:117], v[92:93]
	v_pk_add_f32 v[104:105], v[104:105], v[106:107]
	v_pk_add_f32 v[106:107], v[108:109], v[110:111]
	v_mov_b32_e32 v108, v92
	v_pk_add_f32 v[104:105], v[104:105], v[106:107]
	v_pk_mov_b32 v[106:107], v[92:93], v[90:91] op_sel:[1,0]
	v_mov_b32_e32 v109, v91
	v_pk_add_f32 v[106:107], v[106:107], v[108:109]
	v_pk_add_f32 v[104:105], v[104:105], v[104:105] op_sel:[0,1] op_sel_hi:[1,0]
	v_pk_add_f32 v[106:107], v[106:107], v[106:107] op_sel:[0,1] op_sel_hi:[1,0]
	v_add_f32_e32 v108, v96, v97
	v_add_f32_e32 v110, v94, v95
	v_mov_b32_e32 v105, v100
	v_mov_b32_e32 v107, v101
	v_mov_b32_e32 v109, v98
	v_mov_b32_e32 v111, v99
	v_pk_add_f32 v[104:105], v[104:105], v[106:107]
	v_pk_add_f32 v[106:107], v[108:109], v[110:111]
	s_nop 0
	v_pk_add_f32 v[104:105], v[104:105], v[106:107]
	v_xor_b32_e32 v106, 1, v185
	v_add_f32_e32 v104, v104, v105
	v_and_b32_e32 v105, 64, v185
	v_add_u32_e32 v105, 64, v105
	v_cmp_lt_i32_e32 vcc, v106, v105
	s_nop 1
	v_cndmask_b32_e32 v106, v185, v106, vcc
	v_lshlrev_b32_e32 v112, 2, v106
	ds_bpermute_b32 v106, v112, v104
	s_waitcnt lgkmcnt(0)
	v_add_f32_e32 v104, v104, v106
	v_xor_b32_e32 v106, 2, v185
	v_cmp_lt_i32_e32 vcc, v106, v105
	s_nop 1
	v_cndmask_b32_e32 v106, v185, v106, vcc
	v_lshlrev_b32_e32 v113, 2, v106
	ds_bpermute_b32 v106, v113, v104
	s_waitcnt lgkmcnt(0)
	v_add_f32_e32 v104, v104, v106
	v_xor_b32_e32 v106, 4, v185
	v_cmp_lt_i32_e32 vcc, v106, v105
	s_nop 1
	v_cndmask_b32_e32 v106, v185, v106, vcc
	v_lshlrev_b32_e32 v114, 2, v106
	ds_bpermute_b32 v106, v114, v104
	s_waitcnt lgkmcnt(0)
	v_add_f32_e32 v104, v104, v106
	v_xor_b32_e32 v106, 8, v185
	v_cmp_lt_i32_e32 vcc, v106, v105
	s_nop 1
	v_cndmask_b32_e32 v106, v185, v106, vcc
	v_lshlrev_b32_e32 v115, 2, v106
	ds_bpermute_b32 v106, v115, v104
	s_waitcnt lgkmcnt(0)
	v_add_f32_e32 v104, v104, v106
	v_xor_b32_e32 v106, 16, v185
	v_cmp_lt_i32_e32 vcc, v106, v105
	s_nop 1
	v_cndmask_b32_e32 v106, v185, v106, vcc
	v_lshlrev_b32_e32 v116, 2, v106
	ds_bpermute_b32 v106, v116, v104
	s_waitcnt lgkmcnt(0)
	v_add_f32_e32 v104, v104, v106
	v_xor_b32_e32 v106, 32, v185
	v_cmp_lt_i32_e32 vcc, v106, v105
	s_nop 1
	v_cndmask_b32_e32 v105, v185, v106, vcc
	v_lshlrev_b32_e32 v117, 2, v105
	ds_bpermute_b32 v105, v117, v104
	s_waitcnt lgkmcnt(0)
	v_add_f32_e32 v118, v104, v105
	v_fmamk_f32 v73, v118, 0xba000000, v73
	v_fmamk_f32 v77, v118, 0xba000000, v77
	v_fmamk_f32 v71, v118, 0xba000000, v71
	v_fmac_f32_e32 v72, 0xba000000, v118
	v_fmamk_f32 v75, v118, 0xba000000, v75
	v_fmac_f32_e32 v76, 0xba000000, v118
	v_mov_b32_e32 v106, v73
	v_mov_b32_e32 v107, v77
	v_fmac_f32_e32 v70, 0xba000000, v118
	v_fmac_f32_e32 v74, 0xba000000, v118
	v_mov_b32_e32 v104, v72
	v_mov_b32_e32 v105, v76
	v_pk_mul_f32 v[106:107], v[106:107], v[106:107]
	v_mov_b32_e32 v108, v71
	v_mov_b32_e32 v109, v75
	v_pk_fma_f32 v[104:105], v[104:105], v[104:105], v[106:107]
	v_mov_b32_e32 v106, v70
	v_mov_b32_e32 v107, v74
	v_pk_mul_f32 v[108:109], v[108:109], v[108:109]
	v_fmamk_f32 v81, v118, 0xba000000, v81
	v_pk_fma_f32 v[106:107], v[106:107], v[106:107], v[108:109]
	v_fmac_f32_e32 v80, 0xba000000, v118
	v_pk_add_f32 v[104:105], v[104:105], v[106:107]
	v_fmamk_f32 v79, v118, 0xba000000, v79
	v_fmac_f32_e32 v78, 0xba000000, v118
	v_pk_add_f32 v[104:105], v[104:105], v[104:105] op_sel_hi:[0,1]
	v_pk_mul_f32 v[106:107], v[78:79], v[78:79]
	v_pk_mul_f32 v[108:109], v[80:81], v[80:81]
	v_fmac_f32_e32 v84, 0xba000000, v118
	v_pk_mov_b32 v[110:111], v[108:109], v[106:107] op_sel:[1,0]
	v_mov_b32_e32 v109, v107
	v_fmamk_f32 v85, v118, 0xba000000, v85
	v_fmac_f32_e32 v82, 0xba000000, v118
	v_mul_f32_e32 v104, v84, v84
	v_pk_add_f32 v[106:107], v[110:111], v[108:109]
	v_fmamk_f32 v83, v118, 0xba000000, v83
	v_pk_fma_f32 v[108:109], v[84:85], v[84:85], v[104:105] op_sel_hi:[1,1,0]
	v_mul_f32_e32 v104, v82, v82
	v_pk_add_f32 v[106:107], v[106:107], v[106:107] op_sel_hi:[0,1]
	v_pk_fma_f32 v[110:111], v[82:83], v[82:83], v[104:105] op_sel_hi:[1,1,0]
	v_fmamk_f32 v87, v118, 0xba000000, v87
	v_fmac_f32_e32 v86, 0xba000000, v118
	v_fmamk_f32 v89, v118, 0xba000000, v89
	v_fmac_f32_e32 v88, 0xba000000, v118
	v_mul_f32_e32 v108, v88, v88
	v_mul_f32_e32 v110, v89, v89
	v_mul_f32_e32 v106, v86, v86
	v_mul_f32_e32 v104, v87, v87
	v_pk_add_f32 v[108:109], v[108:109], v[110:111]
	v_pk_add_f32 v[104:105], v[106:107], v[104:105]
	v_fmamk_f32 v93, v118, 0xba000000, v93
	v_pk_add_f32 v[104:105], v[108:109], v[104:105]
	v_fmac_f32_e32 v92, 0xba000000, v118
	v_fmamk_f32 v91, v118, 0xba000000, v91
	v_fmac_f32_e32 v90, 0xba000000, v118
	v_pk_add_f32 v[104:105], v[104:105], v[104:105] op_sel_hi:[0,1]
	v_pk_mul_f32 v[106:107], v[90:91], v[90:91]
	v_pk_mul_f32 v[108:109], v[92:93], v[92:93]
	v_fmac_f32_e32 v96, 0xba000000, v118
	v_pk_mov_b32 v[110:111], v[108:109], v[106:107] op_sel:[1,0]
	v_mov_b32_e32 v109, v107
	v_fmamk_f32 v97, v118, 0xba000000, v97
	v_fmac_f32_e32 v94, 0xba000000, v118
	v_mul_f32_e32 v104, v96, v96
	v_pk_add_f32 v[106:107], v[110:111], v[108:109]
	v_fmamk_f32 v95, v118, 0xba000000, v95
	v_pk_fma_f32 v[108:109], v[96:97], v[96:97], v[104:105] op_sel_hi:[1,1,0]
	v_mul_f32_e32 v104, v94, v94
	v_pk_add_f32 v[106:107], v[106:107], v[106:107] op_sel_hi:[0,1]
	v_pk_fma_f32 v[110:111], v[94:95], v[94:95], v[104:105] op_sel_hi:[1,1,0]
	v_fmamk_f32 v99, v118, 0xba000000, v99
	v_fmac_f32_e32 v98, 0xba000000, v118
	v_fmamk_f32 v101, v118, 0xba000000, v101
	v_fmac_f32_e32 v100, 0xba000000, v118
	v_mul_f32_e32 v108, v100, v100
	v_mul_f32_e32 v110, v101, v101
	v_mul_f32_e32 v106, v98, v98
	v_mul_f32_e32 v104, v99, v99
	v_pk_add_f32 v[108:109], v[108:109], v[110:111]
	v_pk_add_f32 v[104:105], v[106:107], v[104:105]
	s_nop 0
	v_pk_add_f32 v[104:105], v[108:109], v[104:105]
	s_nop 0
	v_add_f32_e32 v104, v104, v105
	ds_bpermute_b32 v105, v112, v104
	s_waitcnt lgkmcnt(0)
	v_add_f32_e32 v104, v104, v105
	ds_bpermute_b32 v105, v113, v104
	s_waitcnt lgkmcnt(0)
	v_add_f32_e32 v104, v104, v105
	ds_bpermute_b32 v105, v114, v104
	s_waitcnt lgkmcnt(0)
	v_add_f32_e32 v104, v104, v105
	ds_bpermute_b32 v105, v115, v104
	s_waitcnt lgkmcnt(0)
	v_add_f32_e32 v104, v104, v105
	ds_bpermute_b32 v105, v116, v104
	s_waitcnt lgkmcnt(0)
	v_add_f32_e32 v104, v104, v105
	ds_bpermute_b32 v105, v117, v104
	s_waitcnt lgkmcnt(0)
	v_add_f32_e32 v104, v104, v105
	v_fmamk_f32 v104, v104, 0x3a000000, v181
	v_cmp_gt_f32_e32 vcc, s65, v104
	v_mul_f32_e32 v105, 0x4f800000, v104
	s_nop 0
	v_cndmask_b32_e32 v104, v104, v105, vcc
	v_sqrt_f32_e32 v105, v104
	s_nop 0
	v_add_u32_e32 v106, -1, v105
	v_fma_f32 v107, -v106, v105, v104
	v_cmp_ge_f32_e64 s[0:1], 0, v107
	v_add_u32_e32 v107, 1, v105
	s_nop 0
	v_cndmask_b32_e64 v106, v105, v106, s[0:1]
	v_fma_f32 v105, -v107, v105, v104
	v_cmp_lt_f32_e64 s[0:1], 0, v105
	s_nop 1
	v_cndmask_b32_e64 v105, v106, v107, s[0:1]
	v_mul_f32_e32 v106, 0x37800000, v105
	v_cndmask_b32_e32 v105, v105, v106, vcc
	v_cmp_class_f32_e32 vcc, v104, v182
	s_nop 1
	v_cndmask_b32_e32 v104, v105, v104, vcc
	v_div_scale_f32 v105, s[0:1], v104, v104, 1.0
	v_rcp_f32_e32 v106, v105
	s_nop 0
	v_fma_f32 v107, -v105, v106, 1.0
	v_fmac_f32_e32 v106, v107, v106
	v_div_scale_f32 v107, vcc, 1.0, v104, 1.0
	v_mul_f32_e32 v108, v107, v106
	v_fma_f32 v109, -v105, v108, v107
	v_fmac_f32_e32 v108, v109, v106
	v_fma_f32 v105, -v105, v108, v107
	v_div_fmas_f32 v105, v105, v106, v108
	v_div_fixup_f32 v104, v105, v104, 1.0
	v_pk_mul_f32 v[72:73], v[72:73], v[104:105] op_sel_hi:[1,0]
	v_pk_mul_f32 v[70:71], v[70:71], v[104:105] op_sel_hi:[1,0]
	v_pk_fma_f32 v[72:73], v[2:3], v[72:73], v[6:7]
	v_pk_fma_f32 v[70:71], v[4:5], v[70:71], v[8:9]
	v_pk_mul_f32 v[76:77], v[76:77], v[104:105] op_sel_hi:[1,0]
	v_pk_mul_f32 v[74:75], v[74:75], v[104:105] op_sel_hi:[1,0]
	v_pk_fma_f32 v[76:77], v[10:11], v[76:77], v[14:15]
	v_pk_fma_f32 v[74:75], v[12:13], v[74:75], v[16:17]
	v_pk_mul_f32 v[80:81], v[80:81], v[104:105] op_sel_hi:[1,0]
	v_pk_mul_f32 v[78:79], v[78:79], v[104:105] op_sel_hi:[1,0]
	v_cvt_pk_bf16_f32 v72, v72, v73
	v_cvt_pk_bf16_f32 v73, v70, v71
	v_pk_fma_f32 v[78:79], v[20:21], v[78:79], v[24:25]
	v_pk_fma_f32 v[80:81], v[18:19], v[80:81], v[22:23]
	v_pk_mul_f32 v[84:85], v[84:85], v[104:105] op_sel_hi:[1,0]
	v_pk_mul_f32 v[82:83], v[82:83], v[104:105] op_sel_hi:[1,0]
	global_store_dwordx2 v[68:69], v[72:73], off
	v_cvt_pk_bf16_f32 v68, v76, v77
	v_cvt_pk_bf16_f32 v69, v74, v75
	v_pk_fma_f32 v[82:83], v[28:29], v[82:83], v[32:33]
	v_pk_fma_f32 v[84:85], v[26:27], v[84:85], v[30:31]
	v_pk_mul_f32 v[88:89], v[88:89], v[104:105] op_sel_hi:[1,0]
	v_pk_mul_f32 v[86:87], v[86:87], v[104:105] op_sel_hi:[1,0]
	global_store_dwordx2 v[66:67], v[68:69], off offset:512
	v_cvt_pk_bf16_f32 v68, v80, v81
	v_cvt_pk_bf16_f32 v69, v78, v79
	v_pk_fma_f32 v[86:87], v[36:37], v[86:87], v[40:41]
	v_pk_fma_f32 v[88:89], v[34:35], v[88:89], v[38:39]
	v_pk_mul_f32 v[92:93], v[92:93], v[104:105] op_sel_hi:[1,0]
	v_pk_mul_f32 v[90:91], v[90:91], v[104:105] op_sel_hi:[1,0]
	global_store_dwordx2 v[66:67], v[68:69], off offset:1024
	v_cvt_pk_bf16_f32 v68, v84, v85
	v_cvt_pk_bf16_f32 v69, v82, v83
	v_pk_fma_f32 v[90:91], v[44:45], v[90:91], v[48:49]
	v_pk_fma_f32 v[92:93], v[42:43], v[92:93], v[46:47]
	v_pk_mul_f32 v[96:97], v[96:97], v[104:105] op_sel_hi:[1,0]
	v_pk_mul_f32 v[94:95], v[94:95], v[104:105] op_sel_hi:[1,0]
	global_store_dwordx2 v[66:67], v[68:69], off offset:1536
	v_cvt_pk_bf16_f32 v68, v88, v89
	v_cvt_pk_bf16_f32 v69, v86, v87
	v_pk_fma_f32 v[94:95], v[52:53], v[94:95], v[56:57]
	v_pk_fma_f32 v[96:97], v[50:51], v[96:97], v[54:55]
	v_pk_mul_f32 v[100:101], v[100:101], v[104:105] op_sel_hi:[1,0]
	v_pk_mul_f32 v[98:99], v[98:99], v[104:105] op_sel_hi:[1,0]
	global_store_dwordx2 v[66:67], v[68:69], off offset:2048
	v_cvt_pk_bf16_f32 v68, v92, v93
	v_cvt_pk_bf16_f32 v69, v90, v91
	v_pk_fma_f32 v[98:99], v[60:61], v[98:99], v[64:65]
	v_pk_fma_f32 v[100:101], v[58:59], v[100:101], v[62:63]
	global_store_dwordx2 v[66:67], v[68:69], off offset:2560
	v_cvt_pk_bf16_f32 v68, v96, v97
	v_cvt_pk_bf16_f32 v69, v94, v95
	global_store_dwordx2 v[66:67], v[68:69], off offset:3072
	v_cvt_pk_bf16_f32 v68, v100, v101
	v_cvt_pk_bf16_f32 v69, v98, v99
	global_store_dwordx2 v[66:67], v[68:69], off offset:3584
	s_branch .LBB0_929
